# static s_setprio 1 for waves 4-7 set once before each K-loop (no per-segment toggles), on top of v36
# baseline (speedup 1.0000x reference)
; #define PG8_STAGE(bufoff, gbase, voff) do { _Pragma("unroll") for (int _i = 0; _i < 2; ++_i) \
;         __builtin_amdgcn_global_load_lds((const unsigned*)((const char*)(gbase) + (voff)[_i]), (PG8_LAS unsigned*)(lds + (bufoff) + ldsw + _i * 8192), 16, 0, 0); } while (0)
; #define PG8_LDA(dst, b, h) do { _Pragma("unroll") for (int m = 0; m < 4; ++m) _Pragma("unroll") for (int k = 0; k < 2; ++k) dst[m][k] = *(const PG8_LAS bf16x8*)(lds + PG8_SA(b, h) + aoff + m * 2048 + k * 1024); } while (0)
; #define PG8_LDB(dst, b, h) do { _Pragma("unroll") for (int n = 0; n < 2; ++n) _Pragma("unroll") for (int k = 0; k < 2; ++k) dst[n][k] = *(const PG8_LAS bf16x8*)(lds + PG8_SB(b, h) + boff + n * 2048 + k * 1024); } while (0)
; #define PG8_SCHED __builtin_amdgcn_sched_barrier(0)
; template <class Epi, class Sched, bool ALIGN_EPI = false, bool SP2 = false>
; __device__ __forceinline__ void gemm_phase(PG8_LAS unsigned char* lds, const Gemm g, const Sched& S, const Epi& E) {
;     ...
;         const bool has_next = S.next(ui + 1, nxt);
;         const char* nA = has_next ? (const char*)g.A + (size_t)nxt.pm * tstepA : cA; const char* nB = has_next ? (const char*)g.Bt + (size_t)nxt.pn * tstepB : cB;
;         for (int t = 0; t < nt; t += 2) {
;             const bool last = (t == nt - 2);
;             const char* a1 = cA + (size_t)(t + 1) * kstep;
;             const char* a2 = last ? nA : cA + (size_t)(t + 2) * kstep; const char* b2 = last ? nB : cB + (size_t)(t + 2) * kstep;
;             const char* a3 = a2 + kstep; const char* b3 = b2 + kstep;
;             if (last && has_next) S.a_ready(nxt);
;             if constexpr (SP2) {
;             PG8_LDB(B0, 0, 0); PG8_LDB(B1, 0, 1); PG8_SCHED; PG8_LDA(At, 0, 0); PG8_STAGE(PG8_SA(1, 1), a1 + hstepA, voffA);
;     ...
; #pragma unroll
;         for (int a = 0; a < 2; ++a)
; #pragma unroll
;             for (int b = 0; b < 2; ++b)
; #pragma unroll
;                 for (int m = 0; m < 4; ++m)
; #pragma unroll
;                     for (int n = 0; n < 2; ++n) acc[a][b][m][n] = (f32x4){0.f, 0.f, 0.f, 0.f};
.LBB0_633:
	s_ashr_i32 s17, s16, 31
	s_lshl_b64 s[2:3], s[16:17], 19
	s_add_u32 s66, s58, s2
	s_addc_u32 s67, s59, s3
	s_and_b64 s[2:3], s[4:5], exec
	s_cselect_b32 s17, s67, s1
	s_cselect_b32 s78, s66, s0
	s_ashr_i32 s15, s14, 31
	s_lshl_b64 s[2:3], s[14:15], 19
	v_readlane_b32 s15, v254, 12
	s_add_u32 s82, s15, s2
	v_readlane_b32 s2, v254, 14
	s_addc_u32 s83, s2, s3
	s_and_b64 s[2:3], s[4:5], exec
	s_cselect_b32 s15, s83, s7
	s_cselect_b32 s87, s82, s6
	s_add_u32 s93, s6, 0x100
	s_addc_u32 s94, s7, 0
	s_add_u32 s0, s0, 0x40080
	v_mov_b32_e32 v0, 0
	s_addc_u32 s1, s1, 0
	s_mov_b32 s95, -2
	v_mov_b32_e32 v1, v0
	v_mov_b32_e32 v2, v0
	v_mov_b32_e32 v3, v0
	v_mov_b32_e32 v4, v0
	v_mov_b32_e32 v5, v0
	v_mov_b32_e32 v6, v0
	v_mov_b32_e32 v7, v0
	v_mov_b32_e32 v16, v0
	v_mov_b32_e32 v17, v0
	v_mov_b32_e32 v18, v0
	v_mov_b32_e32 v19, v0
	v_mov_b32_e32 v20, v0
	v_mov_b32_e32 v21, v0
	v_mov_b32_e32 v22, v0
	v_mov_b32_e32 v23, v0
	v_mov_b32_e32 v32, v0
	v_mov_b32_e32 v33, v0
	v_mov_b32_e32 v34, v0
	v_mov_b32_e32 v35, v0
	v_mov_b32_e32 v36, v0
	v_mov_b32_e32 v37, v0
	v_mov_b32_e32 v38, v0
	v_mov_b32_e32 v39, v0
	v_mov_b32_e32 v48, v0
	v_mov_b32_e32 v49, v0
	v_mov_b32_e32 v50, v0
	v_mov_b32_e32 v51, v0
	v_mov_b32_e32 v52, v0
	v_mov_b32_e32 v53, v0
	v_mov_b32_e32 v54, v0
	v_mov_b32_e32 v55, v0
	v_mov_b32_e32 v8, v0
	v_mov_b32_e32 v9, v0
	v_mov_b32_e32 v10, v0
	v_mov_b32_e32 v11, v0
	v_mov_b32_e32 v12, v0
	v_mov_b32_e32 v13, v0
	v_mov_b32_e32 v14, v0
	v_mov_b32_e32 v15, v0
	v_mov_b32_e32 v24, v0
	v_mov_b32_e32 v25, v0
	v_mov_b32_e32 v26, v0
	v_mov_b32_e32 v27, v0
	v_mov_b32_e32 v28, v0
	v_mov_b32_e32 v29, v0
	v_mov_b32_e32 v30, v0
	v_mov_b32_e32 v31, v0
	v_mov_b32_e32 v40, v0
	v_mov_b32_e32 v41, v0
	v_mov_b32_e32 v42, v0
	v_mov_b32_e32 v43, v0
	v_mov_b32_e32 v44, v0
	v_mov_b32_e32 v45, v0
	v_mov_b32_e32 v46, v0
	v_mov_b32_e32 v47, v0
	v_mov_b32_e32 v56, v0
	v_mov_b32_e32 v57, v0
	v_mov_b32_e32 v58, v0
	v_mov_b32_e32 v59, v0
	v_mov_b32_e32 v60, v0
	v_mov_b32_e32 v61, v0
	v_mov_b32_e32 v62, v0
	v_mov_b32_e32 v63, v0
	s_waitcnt vmcnt(0)
	v_mov_b32_e32 v64, v0
	v_mov_b32_e32 v65, v0
	v_mov_b32_e32 v66, v0
	v_mov_b32_e32 v67, v0
	v_mov_b32_e32 v68, v0
	v_mov_b32_e32 v69, v0
	v_mov_b32_e32 v70, v0
	v_mov_b32_e32 v71, v0
	v_mov_b32_e32 v80, v0
	v_mov_b32_e32 v81, v0
	v_mov_b32_e32 v82, v0
	v_mov_b32_e32 v83, v0
	v_mov_b32_e32 v84, v0
	v_mov_b32_e32 v85, v0
	v_mov_b32_e32 v86, v0
	v_mov_b32_e32 v87, v0
	v_mov_b32_e32 v96, v0
	v_mov_b32_e32 v97, v0
	v_mov_b32_e32 v98, v0
	v_mov_b32_e32 v99, v0
	v_mov_b32_e32 v100, v0
	v_mov_b32_e32 v101, v0
	v_mov_b32_e32 v102, v0
	v_mov_b32_e32 v103, v0
	v_mov_b32_e32 v116, v0
	v_mov_b32_e32 v117, v0
	v_mov_b32_e32 v118, v0
	v_mov_b32_e32 v119, v0
	v_mov_b32_e32 v124, v0
	v_mov_b32_e32 v125, v0
	v_mov_b32_e32 v126, v0
	v_mov_b32_e32 v127, v0
	v_mov_b32_e32 v72, v0
	v_mov_b32_e32 v73, v0
	v_mov_b32_e32 v74, v0
	v_mov_b32_e32 v75, v0
	v_mov_b32_e32 v76, v0
	v_mov_b32_e32 v77, v0
	v_mov_b32_e32 v78, v0
	v_mov_b32_e32 v79, v0
	v_mov_b32_e32 v88, v0
	v_mov_b32_e32 v89, v0
	v_mov_b32_e32 v90, v0
	v_mov_b32_e32 v91, v0
	v_mov_b32_e32 v92, v0
	v_mov_b32_e32 v93, v0
	v_mov_b32_e32 v94, v0
	v_mov_b32_e32 v95, v0
	v_mov_b32_e32 v104, v0
	v_mov_b32_e32 v105, v0
	v_mov_b32_e32 v106, v0
	v_mov_b32_e32 v107, v0
	v_mov_b32_e32 v108, v0
	v_mov_b32_e32 v109, v0
	v_mov_b32_e32 v110, v0
	v_mov_b32_e32 v111, v0
	v_mov_b32_e32 v132, v0
	v_mov_b32_e32 v133, v0
	v_mov_b32_e32 v134, v0
	v_mov_b32_e32 v135, v0
	v_mov_b32_e32 v136, v0
	v_mov_b32_e32 v137, v0
	v_mov_b32_e32 v138, v0
	v_mov_b32_e32 v139, v0
	s_cmp_lg_u64 s[10:11], 0
	s_cbranch_scc0 .Lprio_skip4
	s_setprio 1
.Lprio_skip4:
.LBB0_634:
	s_add_u32 s2, s0, 0xfffc0080
	s_addc_u32 s3, s1, -1
	s_add_i32 s30, 0, 0x10000
	s_cmp_eq_u32 s95, 12
	s_cselect_b32 s85, s17, s3
	s_cselect_b32 s84, s78, s2
	s_cselect_b32 s7, s15, s94
	s_cselect_b32 s6, s87, s93
	s_add_i32 s31, 0, 0x14000
	v_add_u32_e32 v140, s30, v230
	v_add_u32_e32 v156, s31, v230
	ds_read_b128 v[112:115], v140
	ds_read_b128 v[120:123], v140 offset:1024
	ds_read_b128 v[128:131], v140 offset:2048
	ds_read_b128 v[140:143], v140 offset:3072
	ds_read_b128 v[144:147], v156
	ds_read_b128 v[148:151], v156 offset:1024
	ds_read_b128 v[152:155], v156 offset:2048
	ds_read_b128 v[156:159], v156 offset:3072
	s_add_i32 m0, s20, 0xc000
	ds_read_b128 v[160:163], v231
	ds_read_b128 v[164:167], v231 offset:1024
	ds_read_b128 v[168:171], v231 offset:2048
	ds_read_b128 v[172:175], v231 offset:3072
	ds_read_b128 v[186:189], v231 offset:4096
	ds_read_b128 v[198:201], v231 offset:5120
	ds_read_b128 v[202:205], v231 offset:6144
	ds_read_b128 v[206:209], v231 offset:7168
	global_load_lds_dwordx4 v184, s[0:1]
	s_add_i32 m0, s20, 0xe000
	s_nop 0
	global_load_lds_dwordx4 v182, s[0:1]
	s_waitcnt vmcnt(8)
	s_waitcnt lgkmcnt(0)
	s_barrier
; #define PG8_STAGE(bufoff, gbase, voff) do { _Pragma("unroll") for (int _i = 0; _i < 2; ++_i) \
;         __builtin_amdgcn_global_load_lds((const unsigned*)((const char*)(gbase) + (voff)[_i]), (PG8_LAS unsigned*)(lds + (bufoff) + ldsw + _i * 8192), 16, 0, 0); } while (0)
; #define PG8_LDA(dst, b, h) do { _Pragma("unroll") for (int m = 0; m < 4; ++m) _Pragma("unroll") for (int k = 0; k < 2; ++k) dst[m][k] = *(const PG8_LAS bf16x8*)(lds + PG8_SA(b, h) + aoff + m * 2048 + k * 1024); } while (0)
; #define PG8_MMA(ai, bj, At, Bt) do { __builtin_amdgcn_s_setprio(1); _Pragma("unroll") for (int m = 0; m < 4; ++m) _Pragma("unroll") for (int n = 0; n < 2; ++n) _Pragma("unroll") for (int k = 0; k < 2; ++k) \
;         acc[ai][bj][m][n] = __builtin_amdgcn_mfma_f32_16x16x32_bf16(Bt[n][k], At[m][k], acc[ai][bj][m][n], 0, 0, 0); __builtin_amdgcn_s_setprio(0); } while (0)
; #define PG8_WAIT_V(n) asm volatile("s_waitcnt vmcnt(" #n ")" ::: "memory")
; #define PG8_WAIT_L(n) asm volatile("s_waitcnt lgkmcnt(" #n ")" ::: "memory")
; #define PG8_BAR __builtin_amdgcn_s_barrier()
; #define PG8_SCHED __builtin_amdgcn_sched_barrier(0)
; template <class Epi, class Sched, bool ALIGN_EPI = false, bool SP2 = false>
; __device__ __forceinline__ void gemm_phase(PG8_LAS unsigned char* lds, const Gemm g, const Sched& S, const Epi& E) {
;     ...
;             PG8_WAIT_V(8); PG8_WAIT_L(0); PG8_BAR; PG8_MMA(0, 0, At, B0); PG8_MMA(0, 1, At, B1); PG8_BAR; PG8_SCHED;
;             PG8_LDA(At, 0, 1); PG8_STAGE(PG8_SB(0, 0), b2, voffB); PG8_STAGE(PG8_SB(0, 1), b2 + hstepB, voffB); PG8_STAGE(PG8_SA(0, 0), a2, voffA);
;             PG8_WAIT_V(8); PG8_WAIT_L(0); PG8_BAR; PG8_MMA(1, 0, At, B0); PG8_MMA(1, 1, At, B1); PG8_BAR; PG8_SCHED;
	s_waitcnt lgkmcnt(0)
	v_mfma_f32_16x16x32_bf16 v[136:139], v[112:115], v[160:163], v[136:139]
	v_mfma_f32_16x16x32_bf16 v[132:135], v[128:131], v[160:163], v[132:135]
	v_mfma_f32_16x16x32_bf16 v[108:111], v[112:115], v[168:171], v[108:111]
	v_mfma_f32_16x16x32_bf16 v[104:107], v[128:131], v[168:171], v[104:107]
	v_mfma_f32_16x16x32_bf16 v[92:95], v[112:115], v[186:189], v[92:95]
	v_mfma_f32_16x16x32_bf16 v[88:91], v[128:131], v[186:189], v[88:91]
	v_mfma_f32_16x16x32_bf16 v[76:79], v[112:115], v[202:205], v[76:79]
	v_mfma_f32_16x16x32_bf16 v[72:75], v[128:131], v[202:205], v[72:75]
	v_mfma_f32_16x16x32_bf16 v[136:139], v[120:123], v[164:167], v[136:139]
	v_mfma_f32_16x16x32_bf16 v[132:135], v[140:143], v[164:167], v[132:135]
	v_mfma_f32_16x16x32_bf16 v[108:111], v[120:123], v[172:175], v[108:111]
	v_mfma_f32_16x16x32_bf16 v[104:107], v[140:143], v[172:175], v[104:107]
	v_mfma_f32_16x16x32_bf16 v[92:95], v[120:123], v[198:201], v[92:95]
	v_mfma_f32_16x16x32_bf16 v[88:91], v[140:143], v[198:201], v[88:91]
	v_mfma_f32_16x16x32_bf16 v[76:79], v[120:123], v[206:209], v[76:79]
	v_mfma_f32_16x16x32_bf16 v[72:75], v[140:143], v[206:209], v[72:75]
	v_mfma_f32_16x16x32_bf16 v[124:127], v[144:147], v[160:163], v[124:127]
	v_mfma_f32_16x16x32_bf16 v[116:119], v[152:155], v[160:163], v[116:119]
	v_mfma_f32_16x16x32_bf16 v[100:103], v[144:147], v[168:171], v[100:103]
	v_mfma_f32_16x16x32_bf16 v[96:99], v[152:155], v[168:171], v[96:99]
	v_mfma_f32_16x16x32_bf16 v[84:87], v[144:147], v[186:189], v[84:87]
	v_mfma_f32_16x16x32_bf16 v[80:83], v[152:155], v[186:189], v[80:83]
	v_mfma_f32_16x16x32_bf16 v[68:71], v[144:147], v[202:205], v[68:71]
	v_mfma_f32_16x16x32_bf16 v[64:67], v[152:155], v[202:205], v[64:67]
	v_mfma_f32_16x16x32_bf16 v[124:127], v[148:151], v[164:167], v[124:127]
	v_mfma_f32_16x16x32_bf16 v[116:119], v[156:159], v[164:167], v[116:119]
	v_mfma_f32_16x16x32_bf16 v[100:103], v[148:151], v[172:175], v[100:103]
	v_mfma_f32_16x16x32_bf16 v[96:99], v[156:159], v[172:175], v[96:99]
	v_mfma_f32_16x16x32_bf16 v[84:87], v[148:151], v[198:201], v[84:87]
	v_mfma_f32_16x16x32_bf16 v[80:83], v[156:159], v[198:201], v[80:83]
	v_mfma_f32_16x16x32_bf16 v[68:71], v[148:151], v[206:209], v[68:71]
	v_mfma_f32_16x16x32_bf16 v[64:67], v[156:159], v[206:209], v[64:67]
	s_barrier
	s_add_i32 s2, s30, s19
	s_mov_b32 m0, s2
	ds_read_b128 v[160:163], v231 offset:16384
	ds_read_b128 v[164:167], v231 offset:17408
	ds_read_b128 v[168:171], v231 offset:18432
	ds_read_b128 v[172:175], v231 offset:19456
	ds_read_b128 v[186:189], v231 offset:20480
	ds_read_b128 v[198:201], v231 offset:21504
	ds_read_b128 v[202:205], v231 offset:22528
	ds_read_b128 v[206:209], v231 offset:23552
	global_load_lds_dwordx4 v192, s[6:7]
	s_add_i32 m0, s2, 0x2000
	s_add_u32 s2, s6, 0x40000
	s_addc_u32 s3, s7, 0
	s_add_i32 s30, s31, s19
	global_load_lds_dwordx4 v176, s[6:7]
	s_mov_b32 m0, s30
	s_nop 0
	global_load_lds_dwordx4 v192, s[2:3]
	s_add_i32 m0, s30, 0x2000
	s_nop 0
	global_load_lds_dwordx4 v176, s[2:3]
	s_mov_b32 m0, s20
	s_nop 0
	global_load_lds_dwordx4 v180, s[84:85]
	s_mov_b32 m0, s21
	s_nop 0
	global_load_lds_dwordx4 v178, s[84:85]
	s_waitcnt vmcnt(8)
	s_waitcnt lgkmcnt(0)
	s_barrier
	s_waitcnt lgkmcnt(0)
	v_mfma_f32_16x16x32_bf16 v[60:63], v[112:115], v[160:163], v[60:63]
	v_mfma_f32_16x16x32_bf16 v[56:59], v[128:131], v[160:163], v[56:59]
	v_mfma_f32_16x16x32_bf16 v[44:47], v[112:115], v[168:171], v[44:47]
	v_mfma_f32_16x16x32_bf16 v[40:43], v[128:131], v[168:171], v[40:43]
	v_mfma_f32_16x16x32_bf16 v[28:31], v[112:115], v[186:189], v[28:31]
	v_mfma_f32_16x16x32_bf16 v[24:27], v[128:131], v[186:189], v[24:27]
	v_mfma_f32_16x16x32_bf16 v[12:15], v[112:115], v[202:205], v[12:15]
	v_mfma_f32_16x16x32_bf16 v[8:11], v[128:131], v[202:205], v[8:11]
	v_mfma_f32_16x16x32_bf16 v[60:63], v[120:123], v[164:167], v[60:63]
	v_mfma_f32_16x16x32_bf16 v[56:59], v[140:143], v[164:167], v[56:59]
	v_mfma_f32_16x16x32_bf16 v[44:47], v[120:123], v[172:175], v[44:47]
	v_mfma_f32_16x16x32_bf16 v[40:43], v[140:143], v[172:175], v[40:43]
	v_mfma_f32_16x16x32_bf16 v[28:31], v[120:123], v[198:201], v[28:31]
	v_mfma_f32_16x16x32_bf16 v[24:27], v[140:143], v[198:201], v[24:27]
	v_mfma_f32_16x16x32_bf16 v[12:15], v[120:123], v[206:209], v[12:15]
	v_mfma_f32_16x16x32_bf16 v[8:11], v[140:143], v[206:209], v[8:11]
	v_mfma_f32_16x16x32_bf16 v[52:55], v[144:147], v[160:163], v[52:55]
	v_mfma_f32_16x16x32_bf16 v[48:51], v[152:155], v[160:163], v[48:51]
	v_mfma_f32_16x16x32_bf16 v[36:39], v[144:147], v[168:171], v[36:39]
	v_mfma_f32_16x16x32_bf16 v[32:35], v[152:155], v[168:171], v[32:35]
	v_mfma_f32_16x16x32_bf16 v[20:23], v[144:147], v[186:189], v[20:23]
	v_mfma_f32_16x16x32_bf16 v[16:19], v[152:155], v[186:189], v[16:19]
	v_mfma_f32_16x16x32_bf16 v[4:7], v[144:147], v[202:205], v[4:7]
	v_mfma_f32_16x16x32_bf16 v[0:3], v[152:155], v[202:205], v[0:3]
	v_mfma_f32_16x16x32_bf16 v[52:55], v[148:151], v[164:167], v[52:55]
	v_mfma_f32_16x16x32_bf16 v[48:51], v[156:159], v[164:167], v[48:51]
	v_mfma_f32_16x16x32_bf16 v[36:39], v[148:151], v[172:175], v[36:39]
	v_mfma_f32_16x16x32_bf16 v[32:35], v[156:159], v[172:175], v[32:35]
	v_mfma_f32_16x16x32_bf16 v[20:23], v[148:151], v[198:201], v[20:23]
	v_mfma_f32_16x16x32_bf16 v[16:19], v[156:159], v[198:201], v[16:19]
	v_mfma_f32_16x16x32_bf16 v[4:7], v[148:151], v[206:209], v[4:7]
	v_mfma_f32_16x16x32_bf16 v[0:3], v[156:159], v[206:209], v[0:3]
	s_barrier
; #define PG8_STAGE(bufoff, gbase, voff) do { _Pragma("unroll") for (int _i = 0; _i < 2; ++_i) \
;         __builtin_amdgcn_global_load_lds((const unsigned*)((const char*)(gbase) + (voff)[_i]), (PG8_LAS unsigned*)(lds + (bufoff) + ldsw + _i * 8192), 16, 0, 0); } while (0)
; #define PG8_LDA(dst, b, h) do { _Pragma("unroll") for (int m = 0; m < 4; ++m) _Pragma("unroll") for (int k = 0; k < 2; ++k) dst[m][k] = *(const PG8_LAS bf16x8*)(lds + PG8_SA(b, h) + aoff + m * 2048 + k * 1024); } while (0)
; #define PG8_LDB(dst, b, h) do { _Pragma("unroll") for (int n = 0; n < 2; ++n) _Pragma("unroll") for (int k = 0; k < 2; ++k) dst[n][k] = *(const PG8_LAS bf16x8*)(lds + PG8_SB(b, h) + boff + n * 2048 + k * 1024); } while (0)
; #define PG8_MMA(ai, bj, At, Bt) do { __builtin_amdgcn_s_setprio(1); _Pragma("unroll") for (int m = 0; m < 4; ++m) _Pragma("unroll") for (int n = 0; n < 2; ++n) _Pragma("unroll") for (int k = 0; k < 2; ++k) \
;         acc[ai][bj][m][n] = __builtin_amdgcn_mfma_f32_16x16x32_bf16(Bt[n][k], At[m][k], acc[ai][bj][m][n], 0, 0, 0); __builtin_amdgcn_s_setprio(0); } while (0)
; #define PG8_WAIT_V(n) asm volatile("s_waitcnt vmcnt(" #n ")" ::: "memory")
; #define PG8_WAIT_L(n) asm volatile("s_waitcnt lgkmcnt(" #n ")" ::: "memory")
; #define PG8_BAR __builtin_amdgcn_s_barrier()
; #define PG8_SCHED __builtin_amdgcn_sched_barrier(0)
; template <class Epi, class Sched, bool ALIGN_EPI = false, bool SP2 = false>
; __device__ __forceinline__ void gemm_phase(PG8_LAS unsigned char* lds, const Gemm g, const Sched& S, const Epi& E) {
;     ...
;             PG8_LDB(B0, 1, 0); PG8_LDB(B1, 1, 1); PG8_SCHED; PG8_LDA(At, 1, 0); PG8_STAGE(PG8_SA(0, 1), a2 + hstepA, voffA);
;             PG8_WAIT_V(8); PG8_WAIT_L(0); PG8_BAR; PG8_MMA(0, 0, At, B0); PG8_MMA(0, 1, At, B1); PG8_BAR; PG8_SCHED;
;             PG8_LDA(At, 1, 1); PG8_STAGE(PG8_SB(1, 0), b3, voffB); PG8_STAGE(PG8_SB(1, 1), b3 + hstepB, voffB); PG8_STAGE(PG8_SA(1, 0), a3, voffA);
;             PG8_WAIT_V(8); PG8_WAIT_L(0); PG8_BAR; PG8_MMA(1, 0, At, B0); PG8_MMA(1, 1, At, B1); PG8_BAR; PG8_SCHED;
;     ...
;         if constexpr (ALIGN_EPI) { if (wr == 0) PG8_BAR; }
	s_add_i32 s30, 0, 0x18000
	s_add_i32 s31, 0, 0x1c000
	v_add_u32_e32 v140, s30, v230
	v_add_u32_e32 v156, s31, v230
	ds_read_b128 v[112:115], v140
	ds_read_b128 v[120:123], v140 offset:1024
	ds_read_b128 v[128:131], v140 offset:2048
	ds_read_b128 v[140:143], v140 offset:3072
	ds_read_b128 v[144:147], v156
	ds_read_b128 v[148:151], v156 offset:1024
	ds_read_b128 v[152:155], v156 offset:2048
	ds_read_b128 v[156:159], v156 offset:3072
	s_add_u32 s2, s84, 0x40000
	s_addc_u32 s3, s85, 0
	s_mov_b32 m0, s45
	ds_read_b128 v[160:163], v231 offset:32768
	ds_read_b128 v[164:167], v231 offset:33792
	ds_read_b128 v[168:171], v231 offset:34816
	ds_read_b128 v[172:175], v231 offset:35840
	ds_read_b128 v[186:189], v231 offset:36864
	ds_read_b128 v[198:201], v231 offset:37888
	ds_read_b128 v[202:205], v231 offset:38912
	ds_read_b128 v[206:209], v231 offset:39936
	global_load_lds_dwordx4 v180, s[2:3]
	s_mov_b32 m0, s49
	s_nop 0
	global_load_lds_dwordx4 v178, s[2:3]
	s_waitcnt vmcnt(8)
	s_waitcnt lgkmcnt(0)
	s_barrier
	s_waitcnt lgkmcnt(0)
	v_mfma_f32_16x16x32_bf16 v[136:139], v[112:115], v[160:163], v[136:139]
	v_mfma_f32_16x16x32_bf16 v[132:135], v[128:131], v[160:163], v[132:135]
	v_mfma_f32_16x16x32_bf16 v[108:111], v[112:115], v[168:171], v[108:111]
	v_mfma_f32_16x16x32_bf16 v[104:107], v[128:131], v[168:171], v[104:107]
	v_mfma_f32_16x16x32_bf16 v[92:95], v[112:115], v[186:189], v[92:95]
	v_mfma_f32_16x16x32_bf16 v[88:91], v[128:131], v[186:189], v[88:91]
	v_mfma_f32_16x16x32_bf16 v[76:79], v[112:115], v[202:205], v[76:79]
	v_mfma_f32_16x16x32_bf16 v[72:75], v[128:131], v[202:205], v[72:75]
	v_mfma_f32_16x16x32_bf16 v[136:139], v[120:123], v[164:167], v[136:139]
	v_mfma_f32_16x16x32_bf16 v[132:135], v[140:143], v[164:167], v[132:135]
	v_mfma_f32_16x16x32_bf16 v[108:111], v[120:123], v[172:175], v[108:111]
	v_mfma_f32_16x16x32_bf16 v[104:107], v[140:143], v[172:175], v[104:107]
	v_mfma_f32_16x16x32_bf16 v[92:95], v[120:123], v[198:201], v[92:95]
	v_mfma_f32_16x16x32_bf16 v[88:91], v[140:143], v[198:201], v[88:91]
	v_mfma_f32_16x16x32_bf16 v[76:79], v[120:123], v[206:209], v[76:79]
	v_mfma_f32_16x16x32_bf16 v[72:75], v[140:143], v[206:209], v[72:75]
	v_mfma_f32_16x16x32_bf16 v[124:127], v[144:147], v[160:163], v[124:127]
	v_mfma_f32_16x16x32_bf16 v[116:119], v[152:155], v[160:163], v[116:119]
	v_mfma_f32_16x16x32_bf16 v[100:103], v[144:147], v[168:171], v[100:103]
	v_mfma_f32_16x16x32_bf16 v[96:99], v[152:155], v[168:171], v[96:99]
	v_mfma_f32_16x16x32_bf16 v[84:87], v[144:147], v[186:189], v[84:87]
	v_mfma_f32_16x16x32_bf16 v[80:83], v[152:155], v[186:189], v[80:83]
	v_mfma_f32_16x16x32_bf16 v[68:71], v[144:147], v[202:205], v[68:71]
	v_mfma_f32_16x16x32_bf16 v[64:67], v[152:155], v[202:205], v[64:67]
	v_mfma_f32_16x16x32_bf16 v[124:127], v[148:151], v[164:167], v[124:127]
	v_mfma_f32_16x16x32_bf16 v[116:119], v[156:159], v[164:167], v[116:119]
	v_mfma_f32_16x16x32_bf16 v[100:103], v[148:151], v[172:175], v[100:103]
	v_mfma_f32_16x16x32_bf16 v[96:99], v[156:159], v[172:175], v[96:99]
	v_mfma_f32_16x16x32_bf16 v[84:87], v[148:151], v[198:201], v[84:87]
	v_mfma_f32_16x16x32_bf16 v[80:83], v[156:159], v[198:201], v[80:83]
	v_mfma_f32_16x16x32_bf16 v[68:71], v[148:151], v[206:209], v[68:71]
	v_mfma_f32_16x16x32_bf16 v[64:67], v[156:159], v[206:209], v[64:67]
	s_barrier
	s_add_i32 s2, s30, s19
	s_add_i32 m0, s2, 0xffffff80
	ds_read_b128 v[160:163], v231 offset:49152
	ds_read_b128 v[164:167], v231 offset:50176
	ds_read_b128 v[168:171], v231 offset:51200
	ds_read_b128 v[172:175], v231 offset:52224
	ds_read_b128 v[186:189], v231 offset:53248
	ds_read_b128 v[198:201], v231 offset:54272
	ds_read_b128 v[202:205], v231 offset:55296
	ds_read_b128 v[206:209], v231 offset:56320
	global_load_lds_dwordx4 v192, s[6:7] offset:128
	s_add_i32 m0, s2, 0x1f80
	s_add_u32 s2, s6, 0x40080
	global_load_lds_dwordx4 v176, s[6:7] offset:128
	s_addc_u32 s3, s7, 0
	s_add_i32 s6, s31, s19
	s_mov_b32 m0, s6
	s_nop 0
	global_load_lds_dwordx4 v192, s[2:3]
	s_add_i32 m0, s6, 0x2000
	s_nop 0
	global_load_lds_dwordx4 v176, s[2:3]
	s_add_i32 m0, s65, 0xffffff80
	s_nop 0
	global_load_lds_dwordx4 v180, s[84:85] offset:128
	s_add_i32 m0, s80, 0xffffff80
	s_nop 0
	global_load_lds_dwordx4 v178, s[84:85] offset:128
	s_waitcnt vmcnt(8)
	s_waitcnt lgkmcnt(0)
	s_barrier
	s_waitcnt lgkmcnt(0)
	v_mfma_f32_16x16x32_bf16 v[60:63], v[112:115], v[160:163], v[60:63]
	v_mfma_f32_16x16x32_bf16 v[56:59], v[128:131], v[160:163], v[56:59]
	v_mfma_f32_16x16x32_bf16 v[44:47], v[112:115], v[168:171], v[44:47]
	v_mfma_f32_16x16x32_bf16 v[40:43], v[128:131], v[168:171], v[40:43]
	v_mfma_f32_16x16x32_bf16 v[28:31], v[112:115], v[186:189], v[28:31]
	v_mfma_f32_16x16x32_bf16 v[24:27], v[128:131], v[186:189], v[24:27]
	v_mfma_f32_16x16x32_bf16 v[12:15], v[112:115], v[202:205], v[12:15]
	v_mfma_f32_16x16x32_bf16 v[8:11], v[128:131], v[202:205], v[8:11]
	v_mfma_f32_16x16x32_bf16 v[60:63], v[120:123], v[164:167], v[60:63]
	v_mfma_f32_16x16x32_bf16 v[56:59], v[140:143], v[164:167], v[56:59]
	v_mfma_f32_16x16x32_bf16 v[44:47], v[120:123], v[172:175], v[44:47]
	v_mfma_f32_16x16x32_bf16 v[40:43], v[140:143], v[172:175], v[40:43]
	v_mfma_f32_16x16x32_bf16 v[28:31], v[120:123], v[198:201], v[28:31]
	v_mfma_f32_16x16x32_bf16 v[24:27], v[140:143], v[198:201], v[24:27]
	v_mfma_f32_16x16x32_bf16 v[12:15], v[120:123], v[206:209], v[12:15]
	v_mfma_f32_16x16x32_bf16 v[8:11], v[140:143], v[206:209], v[8:11]
	v_mfma_f32_16x16x32_bf16 v[52:55], v[144:147], v[160:163], v[52:55]
	v_mfma_f32_16x16x32_bf16 v[48:51], v[152:155], v[160:163], v[48:51]
	v_mfma_f32_16x16x32_bf16 v[36:39], v[144:147], v[168:171], v[36:39]
	v_mfma_f32_16x16x32_bf16 v[32:35], v[152:155], v[168:171], v[32:35]
	v_mfma_f32_16x16x32_bf16 v[20:23], v[144:147], v[186:189], v[20:23]
	v_mfma_f32_16x16x32_bf16 v[16:19], v[152:155], v[186:189], v[16:19]
	v_mfma_f32_16x16x32_bf16 v[4:7], v[144:147], v[202:205], v[4:7]
	v_mfma_f32_16x16x32_bf16 v[0:3], v[152:155], v[202:205], v[0:3]
	v_mfma_f32_16x16x32_bf16 v[52:55], v[148:151], v[164:167], v[52:55]
	v_mfma_f32_16x16x32_bf16 v[48:51], v[156:159], v[164:167], v[48:51]
	v_mfma_f32_16x16x32_bf16 v[36:39], v[148:151], v[172:175], v[36:39]
	v_mfma_f32_16x16x32_bf16 v[32:35], v[156:159], v[172:175], v[32:35]
	v_mfma_f32_16x16x32_bf16 v[20:23], v[148:151], v[198:201], v[20:23]
	v_mfma_f32_16x16x32_bf16 v[16:19], v[156:159], v[198:201], v[16:19]
	v_mfma_f32_16x16x32_bf16 v[4:7], v[148:151], v[206:209], v[4:7]
	v_mfma_f32_16x16x32_bf16 v[0:3], v[156:159], v[206:209], v[0:3]
	s_barrier
	s_add_i32 s95, s95, 2
	s_add_u32 s93, s93, 0x100
	s_addc_u32 s94, s94, 0
	s_add_u32 s0, s0, 0x100
	s_addc_u32 s1, s1, 0
	s_cmp_gt_u32 s95, 13
	s_cbranch_scc0 .LBB0_634
	s_and_b64 vcc, exec, s[12:13]
	s_cbranch_vccz .LBB0_637
	s_barrier

; #define PG8_STAGE(bufoff, gbase, voff) do { _Pragma("unroll") for (int _i = 0; _i < 2; ++_i) \
;         __builtin_amdgcn_global_load_lds((const unsigned*)((const char*)(gbase) + (voff)[_i]), (PG8_LAS unsigned*)(lds + (bufoff) + ldsw + _i * 8192), 16, 0, 0); } while (0)
; #define PG8_LDA(dst, b, h) do { _Pragma("unroll") for (int m = 0; m < 4; ++m) _Pragma("unroll") for (int k = 0; k < 2; ++k) dst[m][k] = *(const PG8_LAS bf16x8*)(lds + PG8_SA(b, h) + aoff + m * 2048 + k * 1024); } while (0)
; #define PG8_LDB(dst, b, h) do { _Pragma("unroll") for (int n = 0; n < 2; ++n) _Pragma("unroll") for (int k = 0; k < 2; ++k) dst[n][k] = *(const PG8_LAS bf16x8*)(lds + PG8_SB(b, h) + boff + n * 2048 + k * 1024); } while (0)
; #define PG8_SCHED __builtin_amdgcn_sched_barrier(0)
; template <class Epi, class Sched, bool ALIGN_EPI = false, bool SP2 = false>
; __device__ __forceinline__ void gemm_phase(PG8_LAS unsigned char* lds, const Gemm g, const Sched& S, const Epi& E) {
;     ...
;         const bool has_next = S.next(ui + 1, nxt);
;         const char* nA = has_next ? (const char*)g.A + (size_t)nxt.pm * tstepA : cA; const char* nB = has_next ? (const char*)g.Bt + (size_t)nxt.pn * tstepB : cB;
;         for (int t = 0; t < nt; t += 2) {
;             const bool last = (t == nt - 2);
;             const char* a1 = cA + (size_t)(t + 1) * kstep;
;             const char* a2 = last ? nA : cA + (size_t)(t + 2) * kstep; const char* b2 = last ? nB : cB + (size_t)(t + 2) * kstep;
;             const char* a3 = a2 + kstep; const char* b3 = b2 + kstep;
;             if (last && has_next) S.a_ready(nxt);
;             if constexpr (SP2) {
;             PG8_LDB(B0, 0, 0); PG8_LDB(B1, 0, 1); PG8_SCHED; PG8_LDA(At, 0, 0); PG8_STAGE(PG8_SA(1, 1), a1 + hstepA, voffA);
;     ...
; #pragma unroll
;         for (int a = 0; a < 2; ++a)
; #pragma unroll
;             for (int b = 0; b < 2; ++b)
; #pragma unroll
;                 for (int m = 0; m < 4; ++m)
; #pragma unroll
;                     for (int n = 0; n < 2; ++n) acc[a][b][m][n] = (f32x4){0.f, 0.f, 0.f, 0.f};
.LBB0_692:
	s_ashr_i32 s17, s16, 31
	s_lshl_b64 s[2:3], s[16:17], 19
	s_add_u32 s66, s58, s2
	s_addc_u32 s67, s59, s3
	s_and_b64 s[2:3], s[0:1], exec
	s_cselect_b32 s17, s67, s5
	s_cselect_b32 s78, s66, s4
	s_ashr_i32 s15, s14, 31
	s_lshl_b64 s[2:3], s[14:15], 19
	s_add_u32 s82, s38, s2
	s_addc_u32 s83, s41, s3
	s_and_b64 s[2:3], s[0:1], exec
	s_cselect_b32 s15, s83, s85
	s_cselect_b32 s89, s82, s84
	s_add_u32 s90, s84, 0x100
	s_addc_u32 s91, s85, 0
	s_add_u32 s4, s4, 0x40080
	v_mov_b32_e32 v0, 0
	s_addc_u32 s5, s5, 0
	s_mov_b32 s92, -2
	v_mov_b32_e32 v1, v0
	v_mov_b32_e32 v2, v0
	v_mov_b32_e32 v3, v0
	v_mov_b32_e32 v4, v0
	v_mov_b32_e32 v5, v0
	v_mov_b32_e32 v6, v0
	v_mov_b32_e32 v7, v0
	v_mov_b32_e32 v16, v0
	v_mov_b32_e32 v17, v0
	v_mov_b32_e32 v18, v0
	v_mov_b32_e32 v19, v0
	v_mov_b32_e32 v20, v0
	v_mov_b32_e32 v21, v0
	v_mov_b32_e32 v22, v0
	v_mov_b32_e32 v23, v0
	v_mov_b32_e32 v32, v0
	v_mov_b32_e32 v33, v0
	v_mov_b32_e32 v34, v0
	v_mov_b32_e32 v35, v0
	v_mov_b32_e32 v36, v0
	v_mov_b32_e32 v37, v0
	v_mov_b32_e32 v38, v0
	v_mov_b32_e32 v39, v0
	v_mov_b32_e32 v48, v0
	v_mov_b32_e32 v49, v0
	v_mov_b32_e32 v50, v0
	v_mov_b32_e32 v51, v0
	v_mov_b32_e32 v52, v0
	v_mov_b32_e32 v53, v0
	v_mov_b32_e32 v54, v0
	v_mov_b32_e32 v55, v0
	v_mov_b32_e32 v8, v0
	v_mov_b32_e32 v9, v0
	v_mov_b32_e32 v10, v0
	v_mov_b32_e32 v11, v0
	v_mov_b32_e32 v12, v0
	v_mov_b32_e32 v13, v0
	v_mov_b32_e32 v14, v0
	v_mov_b32_e32 v15, v0
	v_mov_b32_e32 v24, v0
	v_mov_b32_e32 v25, v0
	v_mov_b32_e32 v26, v0
	v_mov_b32_e32 v27, v0
	v_mov_b32_e32 v28, v0
	v_mov_b32_e32 v29, v0
	v_mov_b32_e32 v30, v0
	v_mov_b32_e32 v31, v0
	v_mov_b32_e32 v40, v0
	v_mov_b32_e32 v41, v0
	v_mov_b32_e32 v42, v0
	v_mov_b32_e32 v43, v0
	v_mov_b32_e32 v44, v0
	v_mov_b32_e32 v45, v0
	v_mov_b32_e32 v46, v0
	v_mov_b32_e32 v47, v0
	v_mov_b32_e32 v56, v0
	v_mov_b32_e32 v57, v0
	v_mov_b32_e32 v58, v0
	v_mov_b32_e32 v59, v0
	v_mov_b32_e32 v60, v0
	v_mov_b32_e32 v61, v0
	v_mov_b32_e32 v62, v0
	v_mov_b32_e32 v63, v0
	s_waitcnt vmcnt(0)
	v_mov_b32_e32 v64, v0
	v_mov_b32_e32 v65, v0
	v_mov_b32_e32 v66, v0
	v_mov_b32_e32 v67, v0
	v_mov_b32_e32 v68, v0
	v_mov_b32_e32 v69, v0
	v_mov_b32_e32 v70, v0
	v_mov_b32_e32 v71, v0
	v_mov_b32_e32 v80, v0
	v_mov_b32_e32 v81, v0
	v_mov_b32_e32 v82, v0
	v_mov_b32_e32 v83, v0
	v_mov_b32_e32 v84, v0
	v_mov_b32_e32 v85, v0
	v_mov_b32_e32 v86, v0
	v_mov_b32_e32 v87, v0
	v_mov_b32_e32 v96, v0
	v_mov_b32_e32 v97, v0
	v_mov_b32_e32 v98, v0
	v_mov_b32_e32 v99, v0
	v_mov_b32_e32 v100, v0
	v_mov_b32_e32 v101, v0
	v_mov_b32_e32 v102, v0
	v_mov_b32_e32 v103, v0
	v_mov_b32_e32 v112, v0
	v_mov_b32_e32 v113, v0
	v_mov_b32_e32 v114, v0
	v_mov_b32_e32 v115, v0
	v_mov_b32_e32 v116, v0
	v_mov_b32_e32 v117, v0
	v_mov_b32_e32 v118, v0
	v_mov_b32_e32 v119, v0
	v_mov_b32_e32 v72, v0
	v_mov_b32_e32 v73, v0
	v_mov_b32_e32 v74, v0
	v_mov_b32_e32 v75, v0
	v_mov_b32_e32 v76, v0
	v_mov_b32_e32 v77, v0
	v_mov_b32_e32 v78, v0
	v_mov_b32_e32 v79, v0
	v_mov_b32_e32 v88, v0
	v_mov_b32_e32 v89, v0
	v_mov_b32_e32 v90, v0
	v_mov_b32_e32 v91, v0
	v_mov_b32_e32 v92, v0
	v_mov_b32_e32 v93, v0
	v_mov_b32_e32 v94, v0
	v_mov_b32_e32 v95, v0
	v_mov_b32_e32 v104, v0
	v_mov_b32_e32 v105, v0
	v_mov_b32_e32 v106, v0
	v_mov_b32_e32 v107, v0
	v_mov_b32_e32 v108, v0
	v_mov_b32_e32 v109, v0
	v_mov_b32_e32 v110, v0
	v_mov_b32_e32 v111, v0
	v_mov_b32_e32 v120, v0
	v_mov_b32_e32 v121, v0
	v_mov_b32_e32 v122, v0
	v_mov_b32_e32 v123, v0
	v_mov_b32_e32 v124, v0
	v_mov_b32_e32 v125, v0
	v_mov_b32_e32 v126, v0
	v_mov_b32_e32 v127, v0
	s_cmp_lg_u64 s[10:11], 0
	s_cbranch_scc0 .Lprio_skip3
	s_setprio 1
.Lprio_skip3:
.LBB0_693:
	s_add_u32 s2, s4, 0xfffc0080
	s_addc_u32 s3, s5, -1
	s_add_i32 s30, 0, 0x10000
	s_cmp_eq_u32 s92, 12
	s_cselect_b32 s87, s17, s3
	s_cselect_b32 s86, s78, s2
	s_cselect_b32 s85, s15, s91
	s_cselect_b32 s84, s89, s90
	s_add_i32 s31, 0, 0x14000
	v_add_u32_e32 v140, s30, v182
	v_add_u32_e32 v166, s31, v182
	ds_read_b128 v[128:131], v140
	ds_read_b128 v[132:135], v140 offset:1024
	ds_read_b128 v[136:139], v140 offset:2048
	ds_read_b128 v[140:143], v140 offset:3072
	ds_read_b128 v[144:147], v166
	ds_read_b128 v[148:151], v166 offset:1024
	ds_read_b128 v[152:155], v166 offset:2048
	ds_read_b128 v[166:169], v166 offset:3072
	s_add_i32 m0, s20, 0xc000
	ds_read_b128 v[170:173], v183
	ds_read_b128 v[174:177], v183 offset:1024
	ds_read_b128 v[178:181], v183 offset:2048
	ds_read_b128 v[184:187], v183 offset:3072
	ds_read_b128 v[188:191], v183 offset:4096
	ds_read_b128 v[198:201], v183 offset:5120
	ds_read_b128 v[202:205], v183 offset:6144
	ds_read_b128 v[206:209], v183 offset:7168
	global_load_lds_dwordx4 v164, s[4:5]
	s_add_i32 m0, s20, 0xe000
	s_nop 0
	global_load_lds_dwordx4 v162, s[4:5]
	s_waitcnt vmcnt(8)
	s_waitcnt lgkmcnt(0)
	s_barrier
; #define PG8_STAGE(bufoff, gbase, voff) do { _Pragma("unroll") for (int _i = 0; _i < 2; ++_i) \
;         __builtin_amdgcn_global_load_lds((const unsigned*)((const char*)(gbase) + (voff)[_i]), (PG8_LAS unsigned*)(lds + (bufoff) + ldsw + _i * 8192), 16, 0, 0); } while (0)
; #define PG8_LDA(dst, b, h) do { _Pragma("unroll") for (int m = 0; m < 4; ++m) _Pragma("unroll") for (int k = 0; k < 2; ++k) dst[m][k] = *(const PG8_LAS bf16x8*)(lds + PG8_SA(b, h) + aoff + m * 2048 + k * 1024); } while (0)
; #define PG8_MMA(ai, bj, At, Bt) do { __builtin_amdgcn_s_setprio(1); _Pragma("unroll") for (int m = 0; m < 4; ++m) _Pragma("unroll") for (int n = 0; n < 2; ++n) _Pragma("unroll") for (int k = 0; k < 2; ++k) \
;         acc[ai][bj][m][n] = __builtin_amdgcn_mfma_f32_16x16x32_bf16(Bt[n][k], At[m][k], acc[ai][bj][m][n], 0, 0, 0); __builtin_amdgcn_s_setprio(0); } while (0)
; #define PG8_WAIT_V(n) asm volatile("s_waitcnt vmcnt(" #n ")" ::: "memory")
; #define PG8_WAIT_L(n) asm volatile("s_waitcnt lgkmcnt(" #n ")" ::: "memory")
; #define PG8_BAR __builtin_amdgcn_s_barrier()
; #define PG8_SCHED __builtin_amdgcn_sched_barrier(0)
; template <class Epi, class Sched, bool ALIGN_EPI = false, bool SP2 = false>
; __device__ __forceinline__ void gemm_phase(PG8_LAS unsigned char* lds, const Gemm g, const Sched& S, const Epi& E) {
;     ...
;             PG8_WAIT_V(8); PG8_WAIT_L(0); PG8_BAR; PG8_MMA(0, 0, At, B0); PG8_MMA(0, 1, At, B1); PG8_BAR; PG8_SCHED;
;             PG8_LDA(At, 0, 1); PG8_STAGE(PG8_SB(0, 0), b2, voffB); PG8_STAGE(PG8_SB(0, 1), b2 + hstepB, voffB); PG8_STAGE(PG8_SA(0, 0), a2, voffA);
;             PG8_WAIT_V(8); PG8_WAIT_L(0); PG8_BAR; PG8_MMA(1, 0, At, B0); PG8_MMA(1, 1, At, B1); PG8_BAR; PG8_SCHED;
	s_waitcnt lgkmcnt(0)
	v_mfma_f32_16x16x32_bf16 v[124:127], v[128:131], v[170:173], v[124:127]
	v_mfma_f32_16x16x32_bf16 v[120:123], v[136:139], v[170:173], v[120:123]
	v_mfma_f32_16x16x32_bf16 v[108:111], v[128:131], v[178:181], v[108:111]
	v_mfma_f32_16x16x32_bf16 v[104:107], v[136:139], v[178:181], v[104:107]
	v_mfma_f32_16x16x32_bf16 v[92:95], v[128:131], v[188:191], v[92:95]
	v_mfma_f32_16x16x32_bf16 v[88:91], v[136:139], v[188:191], v[88:91]
	v_mfma_f32_16x16x32_bf16 v[76:79], v[128:131], v[202:205], v[76:79]
	v_mfma_f32_16x16x32_bf16 v[72:75], v[136:139], v[202:205], v[72:75]
	v_mfma_f32_16x16x32_bf16 v[124:127], v[132:135], v[174:177], v[124:127]
	v_mfma_f32_16x16x32_bf16 v[120:123], v[140:143], v[174:177], v[120:123]
	v_mfma_f32_16x16x32_bf16 v[108:111], v[132:135], v[184:187], v[108:111]
	v_mfma_f32_16x16x32_bf16 v[104:107], v[140:143], v[184:187], v[104:107]
	v_mfma_f32_16x16x32_bf16 v[92:95], v[132:135], v[198:201], v[92:95]
	v_mfma_f32_16x16x32_bf16 v[88:91], v[140:143], v[198:201], v[88:91]
	v_mfma_f32_16x16x32_bf16 v[76:79], v[132:135], v[206:209], v[76:79]
	v_mfma_f32_16x16x32_bf16 v[72:75], v[140:143], v[206:209], v[72:75]
	v_mfma_f32_16x16x32_bf16 v[116:119], v[144:147], v[170:173], v[116:119]
	v_mfma_f32_16x16x32_bf16 v[112:115], v[152:155], v[170:173], v[112:115]
	v_mfma_f32_16x16x32_bf16 v[100:103], v[144:147], v[178:181], v[100:103]
	v_mfma_f32_16x16x32_bf16 v[96:99], v[152:155], v[178:181], v[96:99]
	v_mfma_f32_16x16x32_bf16 v[84:87], v[144:147], v[188:191], v[84:87]
	v_mfma_f32_16x16x32_bf16 v[80:83], v[152:155], v[188:191], v[80:83]
	v_mfma_f32_16x16x32_bf16 v[68:71], v[144:147], v[202:205], v[68:71]
	v_mfma_f32_16x16x32_bf16 v[64:67], v[152:155], v[202:205], v[64:67]
	v_mfma_f32_16x16x32_bf16 v[116:119], v[148:151], v[174:177], v[116:119]
	v_mfma_f32_16x16x32_bf16 v[112:115], v[166:169], v[174:177], v[112:115]
	v_mfma_f32_16x16x32_bf16 v[100:103], v[148:151], v[184:187], v[100:103]
	v_mfma_f32_16x16x32_bf16 v[96:99], v[166:169], v[184:187], v[96:99]
	v_mfma_f32_16x16x32_bf16 v[84:87], v[148:151], v[198:201], v[84:87]
	v_mfma_f32_16x16x32_bf16 v[80:83], v[166:169], v[198:201], v[80:83]
	v_mfma_f32_16x16x32_bf16 v[68:71], v[148:151], v[206:209], v[68:71]
	v_mfma_f32_16x16x32_bf16 v[64:67], v[166:169], v[206:209], v[64:67]
	s_barrier
	s_add_i32 s2, s30, s19
	s_mov_b32 m0, s2
	ds_read_b128 v[170:173], v183 offset:16384
	ds_read_b128 v[174:177], v183 offset:17408
	ds_read_b128 v[178:181], v183 offset:18432
	ds_read_b128 v[184:187], v183 offset:19456
	ds_read_b128 v[188:191], v183 offset:20480
	ds_read_b128 v[198:201], v183 offset:21504
	ds_read_b128 v[202:205], v183 offset:22528
	ds_read_b128 v[206:209], v183 offset:23552
	global_load_lds_dwordx4 v192, s[84:85]
	s_add_i32 m0, s2, 0x2000
	s_add_u32 s2, s84, 0x40000
	s_addc_u32 s3, s85, 0
	s_add_i32 s30, s31, s19
	global_load_lds_dwordx4 v156, s[84:85]
	s_mov_b32 m0, s30
	s_nop 0
	global_load_lds_dwordx4 v192, s[2:3]
	s_add_i32 m0, s30, 0x2000
	s_nop 0
	global_load_lds_dwordx4 v156, s[2:3]
	s_mov_b32 m0, s20
	s_nop 0
	global_load_lds_dwordx4 v160, s[86:87]
	s_mov_b32 m0, s21
	s_nop 0
	global_load_lds_dwordx4 v158, s[86:87]
	s_waitcnt vmcnt(8)
	s_waitcnt lgkmcnt(0)
	s_barrier
	s_waitcnt lgkmcnt(0)
	v_mfma_f32_16x16x32_bf16 v[60:63], v[128:131], v[170:173], v[60:63]
	v_mfma_f32_16x16x32_bf16 v[56:59], v[136:139], v[170:173], v[56:59]
	v_mfma_f32_16x16x32_bf16 v[44:47], v[128:131], v[178:181], v[44:47]
	v_mfma_f32_16x16x32_bf16 v[40:43], v[136:139], v[178:181], v[40:43]
	v_mfma_f32_16x16x32_bf16 v[28:31], v[128:131], v[188:191], v[28:31]
	v_mfma_f32_16x16x32_bf16 v[24:27], v[136:139], v[188:191], v[24:27]
	v_mfma_f32_16x16x32_bf16 v[12:15], v[128:131], v[202:205], v[12:15]
	v_mfma_f32_16x16x32_bf16 v[8:11], v[136:139], v[202:205], v[8:11]
	v_mfma_f32_16x16x32_bf16 v[60:63], v[132:135], v[174:177], v[60:63]
	v_mfma_f32_16x16x32_bf16 v[56:59], v[140:143], v[174:177], v[56:59]
	v_mfma_f32_16x16x32_bf16 v[44:47], v[132:135], v[184:187], v[44:47]
	v_mfma_f32_16x16x32_bf16 v[40:43], v[140:143], v[184:187], v[40:43]
	v_mfma_f32_16x16x32_bf16 v[28:31], v[132:135], v[198:201], v[28:31]
	v_mfma_f32_16x16x32_bf16 v[24:27], v[140:143], v[198:201], v[24:27]
	v_mfma_f32_16x16x32_bf16 v[12:15], v[132:135], v[206:209], v[12:15]
	v_mfma_f32_16x16x32_bf16 v[8:11], v[140:143], v[206:209], v[8:11]
	v_mfma_f32_16x16x32_bf16 v[52:55], v[144:147], v[170:173], v[52:55]
	v_mfma_f32_16x16x32_bf16 v[48:51], v[152:155], v[170:173], v[48:51]
	v_mfma_f32_16x16x32_bf16 v[36:39], v[144:147], v[178:181], v[36:39]
	v_mfma_f32_16x16x32_bf16 v[32:35], v[152:155], v[178:181], v[32:35]
	v_mfma_f32_16x16x32_bf16 v[20:23], v[144:147], v[188:191], v[20:23]
	v_mfma_f32_16x16x32_bf16 v[16:19], v[152:155], v[188:191], v[16:19]
	v_mfma_f32_16x16x32_bf16 v[4:7], v[144:147], v[202:205], v[4:7]
	v_mfma_f32_16x16x32_bf16 v[0:3], v[152:155], v[202:205], v[0:3]
	v_mfma_f32_16x16x32_bf16 v[52:55], v[148:151], v[174:177], v[52:55]
	v_mfma_f32_16x16x32_bf16 v[48:51], v[166:169], v[174:177], v[48:51]
	v_mfma_f32_16x16x32_bf16 v[36:39], v[148:151], v[184:187], v[36:39]
	v_mfma_f32_16x16x32_bf16 v[32:35], v[166:169], v[184:187], v[32:35]
	v_mfma_f32_16x16x32_bf16 v[20:23], v[148:151], v[198:201], v[20:23]
	v_mfma_f32_16x16x32_bf16 v[16:19], v[166:169], v[198:201], v[16:19]
	v_mfma_f32_16x16x32_bf16 v[4:7], v[148:151], v[206:209], v[4:7]
	v_mfma_f32_16x16x32_bf16 v[0:3], v[166:169], v[206:209], v[0:3]
	s_barrier
; #define PG8_STAGE(bufoff, gbase, voff) do { _Pragma("unroll") for (int _i = 0; _i < 2; ++_i) \
;         __builtin_amdgcn_global_load_lds((const unsigned*)((const char*)(gbase) + (voff)[_i]), (PG8_LAS unsigned*)(lds + (bufoff) + ldsw + _i * 8192), 16, 0, 0); } while (0)
; #define PG8_LDA(dst, b, h) do { _Pragma("unroll") for (int m = 0; m < 4; ++m) _Pragma("unroll") for (int k = 0; k < 2; ++k) dst[m][k] = *(const PG8_LAS bf16x8*)(lds + PG8_SA(b, h) + aoff + m * 2048 + k * 1024); } while (0)
; #define PG8_LDB(dst, b, h) do { _Pragma("unroll") for (int n = 0; n < 2; ++n) _Pragma("unroll") for (int k = 0; k < 2; ++k) dst[n][k] = *(const PG8_LAS bf16x8*)(lds + PG8_SB(b, h) + boff + n * 2048 + k * 1024); } while (0)
; #define PG8_MMA(ai, bj, At, Bt) do { __builtin_amdgcn_s_setprio(1); _Pragma("unroll") for (int m = 0; m < 4; ++m) _Pragma("unroll") for (int n = 0; n < 2; ++n) _Pragma("unroll") for (int k = 0; k < 2; ++k) \
;         acc[ai][bj][m][n] = __builtin_amdgcn_mfma_f32_16x16x32_bf16(Bt[n][k], At[m][k], acc[ai][bj][m][n], 0, 0, 0); __builtin_amdgcn_s_setprio(0); } while (0)
; #define PG8_WAIT_V(n) asm volatile("s_waitcnt vmcnt(" #n ")" ::: "memory")
; #define PG8_WAIT_L(n) asm volatile("s_waitcnt lgkmcnt(" #n ")" ::: "memory")
; #define PG8_BAR __builtin_amdgcn_s_barrier()
; #define PG8_SCHED __builtin_amdgcn_sched_barrier(0)
; template <class Epi, class Sched, bool ALIGN_EPI = false, bool SP2 = false>
; __device__ __forceinline__ void gemm_phase(PG8_LAS unsigned char* lds, const Gemm g, const Sched& S, const Epi& E) {
;     ...
;             PG8_LDB(B0, 1, 0); PG8_LDB(B1, 1, 1); PG8_SCHED; PG8_LDA(At, 1, 0); PG8_STAGE(PG8_SA(0, 1), a2 + hstepA, voffA);
;             PG8_WAIT_V(8); PG8_WAIT_L(0); PG8_BAR; PG8_MMA(0, 0, At, B0); PG8_MMA(0, 1, At, B1); PG8_BAR; PG8_SCHED;
;             PG8_LDA(At, 1, 1); PG8_STAGE(PG8_SB(1, 0), b3, voffB); PG8_STAGE(PG8_SB(1, 1), b3 + hstepB, voffB); PG8_STAGE(PG8_SA(1, 0), a3, voffA);
;             PG8_WAIT_V(8); PG8_WAIT_L(0); PG8_BAR; PG8_MMA(1, 0, At, B0); PG8_MMA(1, 1, At, B1); PG8_BAR; PG8_SCHED;
;     ...
;         if constexpr (ALIGN_EPI) { if (wr == 0) PG8_BAR; }
	s_add_i32 s30, 0, 0x18000
	s_add_i32 s31, 0, 0x1c000
	v_add_u32_e32 v140, s30, v182
	v_add_u32_e32 v166, s31, v182
	ds_read_b128 v[128:131], v140
	ds_read_b128 v[132:135], v140 offset:1024
	ds_read_b128 v[136:139], v140 offset:2048
	ds_read_b128 v[140:143], v140 offset:3072
	ds_read_b128 v[144:147], v166
	ds_read_b128 v[148:151], v166 offset:1024
	ds_read_b128 v[152:155], v166 offset:2048
	ds_read_b128 v[166:169], v166 offset:3072
	s_add_u32 s2, s86, 0x40000
	s_addc_u32 s3, s87, 0
	s_mov_b32 m0, s34
	ds_read_b128 v[170:173], v183 offset:32768
	ds_read_b128 v[174:177], v183 offset:33792
	ds_read_b128 v[178:181], v183 offset:34816
	ds_read_b128 v[184:187], v183 offset:35840
	ds_read_b128 v[188:191], v183 offset:36864
	ds_read_b128 v[198:201], v183 offset:37888
	ds_read_b128 v[202:205], v183 offset:38912
	ds_read_b128 v[206:209], v183 offset:39936
	global_load_lds_dwordx4 v160, s[2:3]
	s_mov_b32 m0, s45
	s_nop 0
	global_load_lds_dwordx4 v158, s[2:3]
	s_waitcnt vmcnt(8)
	s_waitcnt lgkmcnt(0)
	s_barrier
	s_waitcnt lgkmcnt(0)
	v_mfma_f32_16x16x32_bf16 v[124:127], v[128:131], v[170:173], v[124:127]
	v_mfma_f32_16x16x32_bf16 v[120:123], v[136:139], v[170:173], v[120:123]
	v_mfma_f32_16x16x32_bf16 v[108:111], v[128:131], v[178:181], v[108:111]
	v_mfma_f32_16x16x32_bf16 v[104:107], v[136:139], v[178:181], v[104:107]
	v_mfma_f32_16x16x32_bf16 v[92:95], v[128:131], v[188:191], v[92:95]
	v_mfma_f32_16x16x32_bf16 v[88:91], v[136:139], v[188:191], v[88:91]
	v_mfma_f32_16x16x32_bf16 v[76:79], v[128:131], v[202:205], v[76:79]
	v_mfma_f32_16x16x32_bf16 v[72:75], v[136:139], v[202:205], v[72:75]
	v_mfma_f32_16x16x32_bf16 v[124:127], v[132:135], v[174:177], v[124:127]
	v_mfma_f32_16x16x32_bf16 v[120:123], v[140:143], v[174:177], v[120:123]
	v_mfma_f32_16x16x32_bf16 v[108:111], v[132:135], v[184:187], v[108:111]
	v_mfma_f32_16x16x32_bf16 v[104:107], v[140:143], v[184:187], v[104:107]
	v_mfma_f32_16x16x32_bf16 v[92:95], v[132:135], v[198:201], v[92:95]
	v_mfma_f32_16x16x32_bf16 v[88:91], v[140:143], v[198:201], v[88:91]
	v_mfma_f32_16x16x32_bf16 v[76:79], v[132:135], v[206:209], v[76:79]
	v_mfma_f32_16x16x32_bf16 v[72:75], v[140:143], v[206:209], v[72:75]
	v_mfma_f32_16x16x32_bf16 v[116:119], v[144:147], v[170:173], v[116:119]
	v_mfma_f32_16x16x32_bf16 v[112:115], v[152:155], v[170:173], v[112:115]
	v_mfma_f32_16x16x32_bf16 v[100:103], v[144:147], v[178:181], v[100:103]
	v_mfma_f32_16x16x32_bf16 v[96:99], v[152:155], v[178:181], v[96:99]
	v_mfma_f32_16x16x32_bf16 v[84:87], v[144:147], v[188:191], v[84:87]
	v_mfma_f32_16x16x32_bf16 v[80:83], v[152:155], v[188:191], v[80:83]
	v_mfma_f32_16x16x32_bf16 v[68:71], v[144:147], v[202:205], v[68:71]
	v_mfma_f32_16x16x32_bf16 v[64:67], v[152:155], v[202:205], v[64:67]
	v_mfma_f32_16x16x32_bf16 v[116:119], v[148:151], v[174:177], v[116:119]
	v_mfma_f32_16x16x32_bf16 v[112:115], v[166:169], v[174:177], v[112:115]
	v_mfma_f32_16x16x32_bf16 v[100:103], v[148:151], v[184:187], v[100:103]
	v_mfma_f32_16x16x32_bf16 v[96:99], v[166:169], v[184:187], v[96:99]
	v_mfma_f32_16x16x32_bf16 v[84:87], v[148:151], v[198:201], v[84:87]
	v_mfma_f32_16x16x32_bf16 v[80:83], v[166:169], v[198:201], v[80:83]
	v_mfma_f32_16x16x32_bf16 v[68:71], v[148:151], v[206:209], v[68:71]
	v_mfma_f32_16x16x32_bf16 v[64:67], v[166:169], v[206:209], v[64:67]
	s_barrier
	s_add_i32 s2, s30, s19
	s_add_i32 m0, s2, 0xffffff80
	ds_read_b128 v[170:173], v183 offset:49152
	ds_read_b128 v[174:177], v183 offset:50176
	ds_read_b128 v[178:181], v183 offset:51200
	ds_read_b128 v[184:187], v183 offset:52224
	ds_read_b128 v[188:191], v183 offset:53248
	ds_read_b128 v[198:201], v183 offset:54272
	ds_read_b128 v[202:205], v183 offset:55296
	ds_read_b128 v[206:209], v183 offset:56320
	global_load_lds_dwordx4 v192, s[84:85] offset:128
	s_add_i32 m0, s2, 0x1f80
	s_add_u32 s2, s84, 0x40080
	s_addc_u32 s3, s85, 0
	s_add_i32 s30, s31, s19
	global_load_lds_dwordx4 v156, s[84:85] offset:128
	s_mov_b32 m0, s30
	s_nop 0
	global_load_lds_dwordx4 v192, s[2:3]
	s_add_i32 m0, s30, 0x2000
	s_nop 0
	global_load_lds_dwordx4 v156, s[2:3]
	s_add_i32 m0, s63, 0xffffff80
	s_nop 0
	global_load_lds_dwordx4 v160, s[86:87] offset:128
	s_add_i32 m0, s64, 0xffffff80
	s_nop 0
	global_load_lds_dwordx4 v158, s[86:87] offset:128
	s_waitcnt vmcnt(8)
	s_waitcnt lgkmcnt(0)
	s_barrier
	s_waitcnt lgkmcnt(0)
	v_mfma_f32_16x16x32_bf16 v[60:63], v[128:131], v[170:173], v[60:63]
	v_mfma_f32_16x16x32_bf16 v[56:59], v[136:139], v[170:173], v[56:59]
	v_mfma_f32_16x16x32_bf16 v[44:47], v[128:131], v[178:181], v[44:47]
	v_mfma_f32_16x16x32_bf16 v[40:43], v[136:139], v[178:181], v[40:43]
	v_mfma_f32_16x16x32_bf16 v[28:31], v[128:131], v[188:191], v[28:31]
	v_mfma_f32_16x16x32_bf16 v[24:27], v[136:139], v[188:191], v[24:27]
	v_mfma_f32_16x16x32_bf16 v[12:15], v[128:131], v[202:205], v[12:15]
	v_mfma_f32_16x16x32_bf16 v[8:11], v[136:139], v[202:205], v[8:11]
	v_mfma_f32_16x16x32_bf16 v[60:63], v[132:135], v[174:177], v[60:63]
	v_mfma_f32_16x16x32_bf16 v[56:59], v[140:143], v[174:177], v[56:59]
	v_mfma_f32_16x16x32_bf16 v[44:47], v[132:135], v[184:187], v[44:47]
	v_mfma_f32_16x16x32_bf16 v[40:43], v[140:143], v[184:187], v[40:43]
	v_mfma_f32_16x16x32_bf16 v[28:31], v[132:135], v[198:201], v[28:31]
	v_mfma_f32_16x16x32_bf16 v[24:27], v[140:143], v[198:201], v[24:27]
	v_mfma_f32_16x16x32_bf16 v[12:15], v[132:135], v[206:209], v[12:15]
	v_mfma_f32_16x16x32_bf16 v[8:11], v[140:143], v[206:209], v[8:11]
	v_mfma_f32_16x16x32_bf16 v[52:55], v[144:147], v[170:173], v[52:55]
	v_mfma_f32_16x16x32_bf16 v[48:51], v[152:155], v[170:173], v[48:51]
	v_mfma_f32_16x16x32_bf16 v[36:39], v[144:147], v[178:181], v[36:39]
	v_mfma_f32_16x16x32_bf16 v[32:35], v[152:155], v[178:181], v[32:35]
	v_mfma_f32_16x16x32_bf16 v[20:23], v[144:147], v[188:191], v[20:23]
	v_mfma_f32_16x16x32_bf16 v[16:19], v[152:155], v[188:191], v[16:19]
	v_mfma_f32_16x16x32_bf16 v[4:7], v[144:147], v[202:205], v[4:7]
	v_mfma_f32_16x16x32_bf16 v[0:3], v[152:155], v[202:205], v[0:3]
	v_mfma_f32_16x16x32_bf16 v[52:55], v[148:151], v[174:177], v[52:55]
	v_mfma_f32_16x16x32_bf16 v[48:51], v[166:169], v[174:177], v[48:51]
	v_mfma_f32_16x16x32_bf16 v[36:39], v[148:151], v[184:187], v[36:39]
	v_mfma_f32_16x16x32_bf16 v[32:35], v[166:169], v[184:187], v[32:35]
	v_mfma_f32_16x16x32_bf16 v[20:23], v[148:151], v[198:201], v[20:23]
	v_mfma_f32_16x16x32_bf16 v[16:19], v[166:169], v[198:201], v[16:19]
	v_mfma_f32_16x16x32_bf16 v[4:7], v[148:151], v[206:209], v[4:7]
	v_mfma_f32_16x16x32_bf16 v[0:3], v[166:169], v[206:209], v[0:3]
	s_barrier
	s_add_i32 s92, s92, 2
	s_add_u32 s90, s90, 0x100
	s_addc_u32 s91, s91, 0
	s_add_u32 s4, s4, 0x100
	s_addc_u32 s5, s5, 0
	s_cmp_gt_u32 s92, 13
	s_cbranch_scc0 .LBB0_693
	s_and_b64 vcc, exec, s[12:13]
	s_cbranch_vccz .LBB0_696
	s_barrier

; #define PG8_STAGE(bufoff, gbase, voff) do { _Pragma("unroll") for (int _i = 0; _i < 2; ++_i) \
;         __builtin_amdgcn_global_load_lds((const unsigned*)((const char*)(gbase) + (voff)[_i]), (PG8_LAS unsigned*)(lds + (bufoff) + ldsw + _i * 8192), 16, 0, 0); } while (0)
; #define PG8_LDA(dst, b, h) do { _Pragma("unroll") for (int m = 0; m < 4; ++m) _Pragma("unroll") for (int k = 0; k < 2; ++k) dst[m][k] = *(const PG8_LAS bf16x8*)(lds + PG8_SA(b, h) + aoff + m * 2048 + k * 1024); } while (0)
; #define PG8_LDB(dst, b, h) do { _Pragma("unroll") for (int n = 0; n < 2; ++n) _Pragma("unroll") for (int k = 0; k < 2; ++k) dst[n][k] = *(const PG8_LAS bf16x8*)(lds + PG8_SB(b, h) + boff + n * 2048 + k * 1024); } while (0)
; #define PG8_WAIT_V(n) asm volatile("s_waitcnt vmcnt(" #n ")" ::: "memory")
; #define PG8_WAIT_L(n) asm volatile("s_waitcnt lgkmcnt(" #n ")" ::: "memory")
; #define PG8_BAR __builtin_amdgcn_s_barrier()
; template <class Epi, class Sched, bool ALIGN_EPI = false, bool SP2 = false>
; __device__ __forceinline__ void gemm_phase(PG8_LAS unsigned char* lds, const Gemm g, const Sched& S, const Epi& E) {
;     ...
;         const bool has_next = S.next(ui + 1, nxt);
;         const char* nA = has_next ? (const char*)g.A + (size_t)nxt.pm * tstepA : cA; const char* nB = has_next ? (const char*)g.Bt + (size_t)nxt.pn * tstepB : cB;
;         for (int t = 0; t < nt; t += 2) {
;             const bool last = (t == nt - 2);
;             const char* a1 = cA + (size_t)(t + 1) * kstep;
;             const char* a2 = last ? nA : cA + (size_t)(t + 2) * kstep; const char* b2 = last ? nB : cB + (size_t)(t + 2) * kstep;
;             const char* a3 = a2 + kstep; const char* b3 = b2 + kstep;
;             if (last && has_next) S.a_ready(nxt);
;             if constexpr (SP2) {
;             PG8_LDB(B0, 0, 0); PG8_LDB(B1, 0, 1); PG8_SCHED; PG8_LDA(At, 0, 0); PG8_STAGE(PG8_SA(1, 1), a1 + hstepA, voffA);
;             PG8_WAIT_V(8); PG8_WAIT_L(0); PG8_BAR; PG8_MMA(0, 0, At, B0); PG8_MMA(0, 1, At, B1); PG8_BAR; PG8_SCHED;
;     ...
; #pragma unroll
;         for (int a = 0; a < 2; ++a)
; #pragma unroll
;             for (int b = 0; b < 2; ++b)
; #pragma unroll
;                 for (int m = 0; m < 4; ++m)
; #pragma unroll
;                     for (int n = 0; n < 2; ++n) acc[a][b][m][n] = (f32x4){0.f, 0.f, 0.f, 0.f};
;         cur = nxt; cA = nA; cB = nB; ++ui;
.LBB0_723:
	s_add_u32 vcc_lo, s82, 0x100
	s_addc_u32 vcc_hi, s83, 0
	s_add_u32 s82, s84, 0x80
	v_mov_b32_e32 v0, 0
	s_addc_u32 s83, s85, 0
	s_mov_b32 s84, 0
	v_mov_b32_e32 v1, v0
	v_mov_b32_e32 v2, v0
	v_mov_b32_e32 v3, v0
	v_mov_b32_e32 v4, v0
	v_mov_b32_e32 v5, v0
	v_mov_b32_e32 v6, v0
	v_mov_b32_e32 v7, v0
	v_mov_b32_e32 v16, v0
	v_mov_b32_e32 v17, v0
	v_mov_b32_e32 v18, v0
	v_mov_b32_e32 v19, v0
	v_mov_b32_e32 v20, v0
	v_mov_b32_e32 v21, v0
	v_mov_b32_e32 v22, v0
	v_mov_b32_e32 v23, v0
	v_mov_b32_e32 v32, v0
	v_mov_b32_e32 v33, v0
	v_mov_b32_e32 v34, v0
	v_mov_b32_e32 v35, v0
	v_mov_b32_e32 v36, v0
	v_mov_b32_e32 v37, v0
	v_mov_b32_e32 v38, v0
	v_mov_b32_e32 v39, v0
	v_mov_b32_e32 v48, v0
	v_mov_b32_e32 v49, v0
	v_mov_b32_e32 v50, v0
	v_mov_b32_e32 v51, v0
	v_mov_b32_e32 v52, v0
	v_mov_b32_e32 v53, v0
	v_mov_b32_e32 v54, v0
	v_mov_b32_e32 v55, v0
	v_mov_b32_e32 v8, v0
	v_mov_b32_e32 v9, v0
	v_mov_b32_e32 v10, v0
	v_mov_b32_e32 v11, v0
	v_mov_b32_e32 v12, v0
	v_mov_b32_e32 v13, v0
	v_mov_b32_e32 v14, v0
	v_mov_b32_e32 v15, v0
	v_mov_b32_e32 v24, v0
	v_mov_b32_e32 v25, v0
	v_mov_b32_e32 v26, v0
	v_mov_b32_e32 v27, v0
	v_mov_b32_e32 v28, v0
	v_mov_b32_e32 v29, v0
	v_mov_b32_e32 v30, v0
	v_mov_b32_e32 v31, v0
	v_mov_b32_e32 v40, v0
	v_mov_b32_e32 v41, v0
	v_mov_b32_e32 v42, v0
	v_mov_b32_e32 v43, v0
	v_mov_b32_e32 v44, v0
	v_mov_b32_e32 v45, v0
	v_mov_b32_e32 v46, v0
	v_mov_b32_e32 v47, v0
	v_mov_b32_e32 v56, v0
	v_mov_b32_e32 v57, v0
	v_mov_b32_e32 v58, v0
	v_mov_b32_e32 v59, v0
	v_mov_b32_e32 v60, v0
	v_mov_b32_e32 v61, v0
	v_mov_b32_e32 v62, v0
	v_mov_b32_e32 v63, v0
	s_waitcnt vmcnt(0)
	v_mov_b32_e32 v64, v0
	v_mov_b32_e32 v65, v0
	v_mov_b32_e32 v66, v0
	v_mov_b32_e32 v67, v0
	v_mov_b32_e32 v68, v0
	v_mov_b32_e32 v69, v0
	v_mov_b32_e32 v70, v0
	v_mov_b32_e32 v71, v0
	v_mov_b32_e32 v80, v0
	v_mov_b32_e32 v81, v0
	v_mov_b32_e32 v82, v0
	v_mov_b32_e32 v83, v0
	v_mov_b32_e32 v84, v0
	v_mov_b32_e32 v85, v0
	v_mov_b32_e32 v86, v0
	v_mov_b32_e32 v87, v0
	v_mov_b32_e32 v96, v0
	v_mov_b32_e32 v97, v0
	v_mov_b32_e32 v98, v0
	v_mov_b32_e32 v99, v0
	v_mov_b32_e32 v100, v0
	v_mov_b32_e32 v101, v0
	v_mov_b32_e32 v102, v0
	v_mov_b32_e32 v103, v0
	v_mov_b32_e32 v116, v0
	v_mov_b32_e32 v117, v0
	v_mov_b32_e32 v118, v0
	v_mov_b32_e32 v119, v0
	v_mov_b32_e32 v120, v0
	v_mov_b32_e32 v121, v0
	v_mov_b32_e32 v122, v0
	v_mov_b32_e32 v123, v0
	v_mov_b32_e32 v72, v0
	v_mov_b32_e32 v73, v0
	v_mov_b32_e32 v74, v0
	v_mov_b32_e32 v75, v0
	v_mov_b32_e32 v76, v0
	v_mov_b32_e32 v77, v0
	v_mov_b32_e32 v78, v0
	v_mov_b32_e32 v79, v0
	v_mov_b32_e32 v88, v0
	v_mov_b32_e32 v89, v0
	v_mov_b32_e32 v90, v0
	v_mov_b32_e32 v91, v0
	v_mov_b32_e32 v92, v0
	v_mov_b32_e32 v93, v0
	v_mov_b32_e32 v94, v0
	v_mov_b32_e32 v95, v0
	v_mov_b32_e32 v104, v0
	v_mov_b32_e32 v105, v0
	v_mov_b32_e32 v106, v0
	v_mov_b32_e32 v107, v0
	v_mov_b32_e32 v108, v0
	v_mov_b32_e32 v109, v0
	v_mov_b32_e32 v110, v0
	v_mov_b32_e32 v111, v0
	v_mov_b32_e32 v132, v0
	v_mov_b32_e32 v133, v0
	v_mov_b32_e32 v134, v0
	v_mov_b32_e32 v135, v0
	v_mov_b32_e32 v140, v0
	v_mov_b32_e32 v141, v0
	v_mov_b32_e32 v142, v0
	v_mov_b32_e32 v143, v0
	s_cmp_lg_u64 s[12:13], 0
	s_cbranch_scc0 .Lprio_skip2
	s_setprio 1
.Lprio_skip2:
.LBB0_724:
	s_add_i32 s2, s84, 2
	s_add_u32 s3, s82, 0x80
	s_addc_u32 s30, s83, 0
	s_add_i32 s77, 0, 0x10000
	s_cmp_eq_u32 s93, s84
	s_cselect_b32 s85, s5, s30
	s_cselect_b32 s84, s4, s3
	s_cselect_b32 s31, s67, vcc_hi
	s_cselect_b32 s30, s66, vcc_lo
	s_add_i32 s3, 0, 0x14000
	v_add_u32_e32 v136, s77, v247
	v_add_u32_e32 v156, s3, v247
	ds_read_b128 v[112:115], v136
	ds_read_b128 v[124:127], v136 offset:1024
	ds_read_b128 v[128:131], v136 offset:2048
	ds_read_b128 v[136:139], v136 offset:3072
	ds_read_b128 v[144:147], v156
	ds_read_b128 v[148:151], v156 offset:1024
	ds_read_b128 v[152:155], v156 offset:2048
	ds_read_b128 v[156:159], v156 offset:3072
	s_add_i32 m0, s64, 0xc000
	ds_read_b128 v[160:163], v248
	ds_read_b128 v[164:167], v248 offset:1024
	ds_read_b128 v[168:171], v248 offset:2048
	ds_read_b128 v[172:175], v248 offset:3072
	ds_read_b128 v[176:179], v248 offset:4096
	ds_read_b128 v[180:183], v248 offset:5120
	ds_read_b128 v[184:187], v248 offset:6144
	ds_read_b128 v[188:191], v248 offset:7168
	global_load_lds_dwordx4 v206, s[82:83]
	s_add_i32 m0, s64, 0xe000
	s_nop 0
	global_load_lds_dwordx4 v204, s[82:83]
	s_waitcnt vmcnt(8)
	s_waitcnt lgkmcnt(0)
	s_barrier
	s_waitcnt lgkmcnt(0)
	v_mfma_f32_16x16x32_bf16 v[140:143], v[112:115], v[160:163], v[140:143]
	v_mfma_f32_16x16x32_bf16 v[132:135], v[128:131], v[160:163], v[132:135]
	v_mfma_f32_16x16x32_bf16 v[108:111], v[112:115], v[168:171], v[108:111]
	v_mfma_f32_16x16x32_bf16 v[104:107], v[128:131], v[168:171], v[104:107]
	v_mfma_f32_16x16x32_bf16 v[92:95], v[112:115], v[176:179], v[92:95]
	v_mfma_f32_16x16x32_bf16 v[88:91], v[128:131], v[176:179], v[88:91]
	v_mfma_f32_16x16x32_bf16 v[76:79], v[112:115], v[184:187], v[76:79]
	v_mfma_f32_16x16x32_bf16 v[72:75], v[128:131], v[184:187], v[72:75]
	v_mfma_f32_16x16x32_bf16 v[140:143], v[124:127], v[164:167], v[140:143]
	v_mfma_f32_16x16x32_bf16 v[132:135], v[136:139], v[164:167], v[132:135]
	v_mfma_f32_16x16x32_bf16 v[108:111], v[124:127], v[172:175], v[108:111]
	v_mfma_f32_16x16x32_bf16 v[104:107], v[136:139], v[172:175], v[104:107]
	v_mfma_f32_16x16x32_bf16 v[92:95], v[124:127], v[180:183], v[92:95]
	v_mfma_f32_16x16x32_bf16 v[88:91], v[136:139], v[180:183], v[88:91]
	v_mfma_f32_16x16x32_bf16 v[76:79], v[124:127], v[188:191], v[76:79]
	v_mfma_f32_16x16x32_bf16 v[72:75], v[136:139], v[188:191], v[72:75]
	v_mfma_f32_16x16x32_bf16 v[120:123], v[144:147], v[160:163], v[120:123]
	v_mfma_f32_16x16x32_bf16 v[116:119], v[152:155], v[160:163], v[116:119]
	v_mfma_f32_16x16x32_bf16 v[100:103], v[144:147], v[168:171], v[100:103]
	v_mfma_f32_16x16x32_bf16 v[96:99], v[152:155], v[168:171], v[96:99]
	v_mfma_f32_16x16x32_bf16 v[84:87], v[144:147], v[176:179], v[84:87]
	v_mfma_f32_16x16x32_bf16 v[80:83], v[152:155], v[176:179], v[80:83]
	v_mfma_f32_16x16x32_bf16 v[68:71], v[144:147], v[184:187], v[68:71]
	v_mfma_f32_16x16x32_bf16 v[64:67], v[152:155], v[184:187], v[64:67]
	v_mfma_f32_16x16x32_bf16 v[120:123], v[148:151], v[164:167], v[120:123]
	v_mfma_f32_16x16x32_bf16 v[116:119], v[156:159], v[164:167], v[116:119]
	v_mfma_f32_16x16x32_bf16 v[100:103], v[148:151], v[172:175], v[100:103]
	v_mfma_f32_16x16x32_bf16 v[96:99], v[156:159], v[172:175], v[96:99]
	v_mfma_f32_16x16x32_bf16 v[84:87], v[148:151], v[180:183], v[84:87]
	v_mfma_f32_16x16x32_bf16 v[80:83], v[156:159], v[180:183], v[80:83]
	v_mfma_f32_16x16x32_bf16 v[68:71], v[148:151], v[188:191], v[68:71]
	v_mfma_f32_16x16x32_bf16 v[64:67], v[156:159], v[188:191], v[64:67]
	s_barrier
; #define PG8_STAGE(bufoff, gbase, voff) do { _Pragma("unroll") for (int _i = 0; _i < 2; ++_i) \
;         __builtin_amdgcn_global_load_lds((const unsigned*)((const char*)(gbase) + (voff)[_i]), (PG8_LAS unsigned*)(lds + (bufoff) + ldsw + _i * 8192), 16, 0, 0); } while (0)
; #define PG8_LDA(dst, b, h) do { _Pragma("unroll") for (int m = 0; m < 4; ++m) _Pragma("unroll") for (int k = 0; k < 2; ++k) dst[m][k] = *(const PG8_LAS bf16x8*)(lds + PG8_SA(b, h) + aoff + m * 2048 + k * 1024); } while (0)
; #define PG8_LDB(dst, b, h) do { _Pragma("unroll") for (int n = 0; n < 2; ++n) _Pragma("unroll") for (int k = 0; k < 2; ++k) dst[n][k] = *(const PG8_LAS bf16x8*)(lds + PG8_SB(b, h) + boff + n * 2048 + k * 1024); } while (0)
; #define PG8_MMA(ai, bj, At, Bt) do { __builtin_amdgcn_s_setprio(1); _Pragma("unroll") for (int m = 0; m < 4; ++m) _Pragma("unroll") for (int n = 0; n < 2; ++n) _Pragma("unroll") for (int k = 0; k < 2; ++k) \
;         acc[ai][bj][m][n] = __builtin_amdgcn_mfma_f32_16x16x32_bf16(Bt[n][k], At[m][k], acc[ai][bj][m][n], 0, 0, 0); __builtin_amdgcn_s_setprio(0); } while (0)
; #define PG8_WAIT_V(n) asm volatile("s_waitcnt vmcnt(" #n ")" ::: "memory")
; #define PG8_WAIT_L(n) asm volatile("s_waitcnt lgkmcnt(" #n ")" ::: "memory")
; #define PG8_BAR __builtin_amdgcn_s_barrier()
; #define PG8_SCHED __builtin_amdgcn_sched_barrier(0)
; template <class Epi, class Sched, bool ALIGN_EPI = false, bool SP2 = false>
; __device__ __forceinline__ void gemm_phase(PG8_LAS unsigned char* lds, const Gemm g, const Sched& S, const Epi& E) {
;     ...
;             PG8_LDA(At, 0, 1); PG8_STAGE(PG8_SB(0, 0), b2, voffB); PG8_STAGE(PG8_SB(0, 1), b2 + hstepB, voffB); PG8_STAGE(PG8_SA(0, 0), a2, voffA);
;             PG8_WAIT_V(8); PG8_WAIT_L(0); PG8_BAR; PG8_MMA(1, 0, At, B0); PG8_MMA(1, 1, At, B1); PG8_BAR; PG8_SCHED;
;             PG8_LDB(B0, 1, 0); PG8_LDB(B1, 1, 1); PG8_SCHED; PG8_LDA(At, 1, 0); PG8_STAGE(PG8_SA(0, 1), a2 + hstepA, voffA);
	s_add_i32 s77, s77, s63
	v_lshl_add_u64 v[208:209], s[30:31], 0, v[192:193]
	s_mov_b32 m0, s77
	ds_read_b128 v[160:163], v248 offset:16384
	ds_read_b128 v[164:167], v248 offset:17408
	ds_read_b128 v[168:171], v248 offset:18432
	ds_read_b128 v[172:175], v248 offset:19456
	ds_read_b128 v[176:179], v248 offset:20480
	ds_read_b128 v[180:183], v248 offset:21504
	ds_read_b128 v[184:187], v248 offset:22528
	ds_read_b128 v[188:191], v248 offset:23552
	global_load_lds_dwordx4 v192, s[30:31]
	s_add_i32 m0, s77, 0x2000
	v_lshl_add_u64 v[210:211], s[30:31], 0, v[198:199]
	global_load_lds_dwordx4 v198, s[30:31]
	s_add_u32 s30, s30, s45
	s_addc_u32 s31, s31, 0
	s_add_i32 s3, s3, s63
	v_lshl_add_u64 v[212:213], s[30:31], 0, v[192:193]
	s_mov_b32 m0, s3
	v_lshl_add_u64 v[214:215], s[30:31], 0, v[198:199]
	global_load_lds_dwordx4 v192, s[30:31]
	s_add_i32 m0, s3, 0x2000
	s_nop 0
	global_load_lds_dwordx4 v198, s[30:31]
	s_mov_b32 m0, s64
	s_nop 0
	global_load_lds_dwordx4 v202, s[84:85]
	s_mov_b32 m0, s65
	s_nop 0
	global_load_lds_dwordx4 v200, s[84:85]
	s_waitcnt vmcnt(8)
	s_waitcnt lgkmcnt(0)
	s_barrier
	s_waitcnt lgkmcnt(0)
	v_mfma_f32_16x16x32_bf16 v[60:63], v[112:115], v[160:163], v[60:63]
	v_mfma_f32_16x16x32_bf16 v[56:59], v[128:131], v[160:163], v[56:59]
	v_mfma_f32_16x16x32_bf16 v[44:47], v[112:115], v[168:171], v[44:47]
	v_mfma_f32_16x16x32_bf16 v[40:43], v[128:131], v[168:171], v[40:43]
	v_mfma_f32_16x16x32_bf16 v[28:31], v[112:115], v[176:179], v[28:31]
	v_mfma_f32_16x16x32_bf16 v[24:27], v[128:131], v[176:179], v[24:27]
	v_mfma_f32_16x16x32_bf16 v[12:15], v[112:115], v[184:187], v[12:15]
	v_mfma_f32_16x16x32_bf16 v[8:11], v[128:131], v[184:187], v[8:11]
	v_mfma_f32_16x16x32_bf16 v[60:63], v[124:127], v[164:167], v[60:63]
	v_mfma_f32_16x16x32_bf16 v[56:59], v[136:139], v[164:167], v[56:59]
	v_mfma_f32_16x16x32_bf16 v[44:47], v[124:127], v[172:175], v[44:47]
	v_mfma_f32_16x16x32_bf16 v[40:43], v[136:139], v[172:175], v[40:43]
	v_mfma_f32_16x16x32_bf16 v[28:31], v[124:127], v[180:183], v[28:31]
	v_mfma_f32_16x16x32_bf16 v[24:27], v[136:139], v[180:183], v[24:27]
	v_mfma_f32_16x16x32_bf16 v[12:15], v[124:127], v[188:191], v[12:15]
	v_mfma_f32_16x16x32_bf16 v[8:11], v[136:139], v[188:191], v[8:11]
	v_mfma_f32_16x16x32_bf16 v[52:55], v[144:147], v[160:163], v[52:55]
	v_mfma_f32_16x16x32_bf16 v[48:51], v[152:155], v[160:163], v[48:51]
	v_mfma_f32_16x16x32_bf16 v[36:39], v[144:147], v[168:171], v[36:39]
	v_mfma_f32_16x16x32_bf16 v[32:35], v[152:155], v[168:171], v[32:35]
	v_mfma_f32_16x16x32_bf16 v[20:23], v[144:147], v[176:179], v[20:23]
	v_mfma_f32_16x16x32_bf16 v[16:19], v[152:155], v[176:179], v[16:19]
	v_mfma_f32_16x16x32_bf16 v[4:7], v[144:147], v[184:187], v[4:7]
	v_mfma_f32_16x16x32_bf16 v[0:3], v[152:155], v[184:187], v[0:3]
	v_mfma_f32_16x16x32_bf16 v[52:55], v[148:151], v[164:167], v[52:55]
	v_mfma_f32_16x16x32_bf16 v[48:51], v[156:159], v[164:167], v[48:51]
	v_mfma_f32_16x16x32_bf16 v[36:39], v[148:151], v[172:175], v[36:39]
	v_mfma_f32_16x16x32_bf16 v[32:35], v[156:159], v[172:175], v[32:35]
	v_mfma_f32_16x16x32_bf16 v[20:23], v[148:151], v[180:183], v[20:23]
	v_mfma_f32_16x16x32_bf16 v[16:19], v[156:159], v[180:183], v[16:19]
	v_mfma_f32_16x16x32_bf16 v[4:7], v[148:151], v[188:191], v[4:7]
	v_mfma_f32_16x16x32_bf16 v[0:3], v[156:159], v[188:191], v[0:3]
	s_barrier
	s_add_i32 s3, 0, 0x18000
	s_add_i32 s77, 0, 0x1c000
	v_add_u32_e32 v136, s3, v247
	v_add_u32_e32 v156, s77, v247
	ds_read_b128 v[112:115], v136
	ds_read_b128 v[124:127], v136 offset:1024
	ds_read_b128 v[128:131], v136 offset:2048
	ds_read_b128 v[136:139], v136 offset:3072
	ds_read_b128 v[144:147], v156
	ds_read_b128 v[148:151], v156 offset:1024
	ds_read_b128 v[152:155], v156 offset:2048
	ds_read_b128 v[156:159], v156 offset:3072
	s_add_u32 s30, s84, s10
	s_addc_u32 s31, s85, 0
	s_mov_b32 m0, s80
	ds_read_b128 v[160:163], v248 offset:32768
	ds_read_b128 v[164:167], v248 offset:33792
	ds_read_b128 v[168:171], v248 offset:34816
	ds_read_b128 v[172:175], v248 offset:35840
	ds_read_b128 v[176:179], v248 offset:36864
	ds_read_b128 v[180:183], v248 offset:37888
	ds_read_b128 v[184:187], v248 offset:38912
	ds_read_b128 v[188:191], v248 offset:39936
	global_load_lds_dwordx4 v202, s[30:31]
	s_mov_b32 m0, s86
	s_nop 0
	global_load_lds_dwordx4 v200, s[30:31]
	s_waitcnt vmcnt(8)
	s_waitcnt lgkmcnt(0)
	s_barrier
; #define PG8_STAGE(bufoff, gbase, voff) do { _Pragma("unroll") for (int _i = 0; _i < 2; ++_i) \
;         __builtin_amdgcn_global_load_lds((const unsigned*)((const char*)(gbase) + (voff)[_i]), (PG8_LAS unsigned*)(lds + (bufoff) + ldsw + _i * 8192), 16, 0, 0); } while (0)
; #define PG8_LDA(dst, b, h) do { _Pragma("unroll") for (int m = 0; m < 4; ++m) _Pragma("unroll") for (int k = 0; k < 2; ++k) dst[m][k] = *(const PG8_LAS bf16x8*)(lds + PG8_SA(b, h) + aoff + m * 2048 + k * 1024); } while (0)
; #define PG8_MMA(ai, bj, At, Bt) do { __builtin_amdgcn_s_setprio(1); _Pragma("unroll") for (int m = 0; m < 4; ++m) _Pragma("unroll") for (int n = 0; n < 2; ++n) _Pragma("unroll") for (int k = 0; k < 2; ++k) \
;         acc[ai][bj][m][n] = __builtin_amdgcn_mfma_f32_16x16x32_bf16(Bt[n][k], At[m][k], acc[ai][bj][m][n], 0, 0, 0); __builtin_amdgcn_s_setprio(0); } while (0)
; #define PG8_WAIT_V(n) asm volatile("s_waitcnt vmcnt(" #n ")" ::: "memory")
; #define PG8_WAIT_L(n) asm volatile("s_waitcnt lgkmcnt(" #n ")" ::: "memory")
; #define PG8_BAR __builtin_amdgcn_s_barrier()
; #define PG8_SCHED __builtin_amdgcn_sched_barrier(0)
; template <class Epi, class Sched, bool ALIGN_EPI = false, bool SP2 = false>
; __device__ __forceinline__ void gemm_phase(PG8_LAS unsigned char* lds, const Gemm g, const Sched& S, const Epi& E) {
;     ...
;             PG8_WAIT_V(8); PG8_WAIT_L(0); PG8_BAR; PG8_MMA(0, 0, At, B0); PG8_MMA(0, 1, At, B1); PG8_BAR; PG8_SCHED;
;             PG8_LDA(At, 1, 1); PG8_STAGE(PG8_SB(1, 0), b3, voffB); PG8_STAGE(PG8_SB(1, 1), b3 + hstepB, voffB); PG8_STAGE(PG8_SA(1, 0), a3, voffA);
;             PG8_WAIT_V(8); PG8_WAIT_L(0); PG8_BAR; PG8_MMA(1, 0, At, B0); PG8_MMA(1, 1, At, B1); PG8_BAR; PG8_SCHED;
;     ...
;         if constexpr (ALIGN_EPI) { if (wr == 0) PG8_BAR; }
	s_waitcnt lgkmcnt(0)
	v_mfma_f32_16x16x32_bf16 v[140:143], v[112:115], v[160:163], v[140:143]
	v_mfma_f32_16x16x32_bf16 v[132:135], v[128:131], v[160:163], v[132:135]
	v_mfma_f32_16x16x32_bf16 v[108:111], v[112:115], v[168:171], v[108:111]
	v_mfma_f32_16x16x32_bf16 v[104:107], v[128:131], v[168:171], v[104:107]
	v_mfma_f32_16x16x32_bf16 v[92:95], v[112:115], v[176:179], v[92:95]
	v_mfma_f32_16x16x32_bf16 v[88:91], v[128:131], v[176:179], v[88:91]
	v_mfma_f32_16x16x32_bf16 v[76:79], v[112:115], v[184:187], v[76:79]
	v_mfma_f32_16x16x32_bf16 v[72:75], v[128:131], v[184:187], v[72:75]
	v_mfma_f32_16x16x32_bf16 v[140:143], v[124:127], v[164:167], v[140:143]
	v_mfma_f32_16x16x32_bf16 v[132:135], v[136:139], v[164:167], v[132:135]
	v_mfma_f32_16x16x32_bf16 v[108:111], v[124:127], v[172:175], v[108:111]
	v_mfma_f32_16x16x32_bf16 v[104:107], v[136:139], v[172:175], v[104:107]
	v_mfma_f32_16x16x32_bf16 v[92:95], v[124:127], v[180:183], v[92:95]
	v_mfma_f32_16x16x32_bf16 v[88:91], v[136:139], v[180:183], v[88:91]
	v_mfma_f32_16x16x32_bf16 v[76:79], v[124:127], v[188:191], v[76:79]
	v_mfma_f32_16x16x32_bf16 v[72:75], v[136:139], v[188:191], v[72:75]
	v_mfma_f32_16x16x32_bf16 v[120:123], v[144:147], v[160:163], v[120:123]
	v_mfma_f32_16x16x32_bf16 v[116:119], v[152:155], v[160:163], v[116:119]
	v_mfma_f32_16x16x32_bf16 v[100:103], v[144:147], v[168:171], v[100:103]
	v_mfma_f32_16x16x32_bf16 v[96:99], v[152:155], v[168:171], v[96:99]
	v_mfma_f32_16x16x32_bf16 v[84:87], v[144:147], v[176:179], v[84:87]
	v_mfma_f32_16x16x32_bf16 v[80:83], v[152:155], v[176:179], v[80:83]
	v_mfma_f32_16x16x32_bf16 v[68:71], v[144:147], v[184:187], v[68:71]
	v_mfma_f32_16x16x32_bf16 v[64:67], v[152:155], v[184:187], v[64:67]
	v_mfma_f32_16x16x32_bf16 v[120:123], v[148:151], v[164:167], v[120:123]
	v_mfma_f32_16x16x32_bf16 v[116:119], v[156:159], v[164:167], v[116:119]
	v_mfma_f32_16x16x32_bf16 v[100:103], v[148:151], v[172:175], v[100:103]
	v_mfma_f32_16x16x32_bf16 v[96:99], v[156:159], v[172:175], v[96:99]
	v_mfma_f32_16x16x32_bf16 v[84:87], v[148:151], v[180:183], v[84:87]
	v_mfma_f32_16x16x32_bf16 v[80:83], v[156:159], v[180:183], v[80:83]
	v_mfma_f32_16x16x32_bf16 v[68:71], v[148:151], v[188:191], v[68:71]
	v_mfma_f32_16x16x32_bf16 v[64:67], v[156:159], v[188:191], v[64:67]
	s_barrier
	s_add_i32 s3, s3, s63
	v_lshl_add_u64 v[208:209], v[208:209], 0, s[36:37]
	s_mov_b32 m0, s3
	ds_read_b128 v[160:163], v248 offset:49152
	ds_read_b128 v[164:167], v248 offset:50176
	ds_read_b128 v[168:171], v248 offset:51200
	ds_read_b128 v[172:175], v248 offset:52224
	ds_read_b128 v[176:179], v248 offset:53248
	ds_read_b128 v[180:183], v248 offset:54272
	ds_read_b128 v[184:187], v248 offset:55296
	ds_read_b128 v[188:191], v248 offset:56320
	global_load_lds_dwordx4 v[208:209], off
	v_lshl_add_u64 v[208:209], v[210:211], 0, s[36:37]
	s_add_i32 m0, s3, 0x2000
	s_add_i32 s3, s77, s63
	global_load_lds_dwordx4 v[208:209], off
	v_lshl_add_u64 v[208:209], v[212:213], 0, s[36:37]
	s_mov_b32 m0, s3
	s_nop 0
	global_load_lds_dwordx4 v[208:209], off
	v_lshl_add_u64 v[208:209], v[214:215], 0, s[36:37]
	s_add_i32 m0, s3, 0x2000
	s_nop 0
	global_load_lds_dwordx4 v[208:209], off
	s_add_i32 m0, s91, 0xffffff80
	s_nop 0
	global_load_lds_dwordx4 v202, s[84:85] offset:128
	s_add_i32 m0, s92, 0xffffff80
	s_nop 0
	global_load_lds_dwordx4 v200, s[84:85] offset:128
	s_waitcnt vmcnt(8)
	s_waitcnt lgkmcnt(0)
	s_barrier
	s_waitcnt lgkmcnt(0)
	v_mfma_f32_16x16x32_bf16 v[60:63], v[112:115], v[160:163], v[60:63]
	v_mfma_f32_16x16x32_bf16 v[56:59], v[128:131], v[160:163], v[56:59]
	v_mfma_f32_16x16x32_bf16 v[44:47], v[112:115], v[168:171], v[44:47]
	v_mfma_f32_16x16x32_bf16 v[40:43], v[128:131], v[168:171], v[40:43]
	v_mfma_f32_16x16x32_bf16 v[28:31], v[112:115], v[176:179], v[28:31]
	v_mfma_f32_16x16x32_bf16 v[24:27], v[128:131], v[176:179], v[24:27]
	v_mfma_f32_16x16x32_bf16 v[12:15], v[112:115], v[184:187], v[12:15]
	v_mfma_f32_16x16x32_bf16 v[8:11], v[128:131], v[184:187], v[8:11]
	v_mfma_f32_16x16x32_bf16 v[60:63], v[124:127], v[164:167], v[60:63]
	v_mfma_f32_16x16x32_bf16 v[56:59], v[136:139], v[164:167], v[56:59]
	v_mfma_f32_16x16x32_bf16 v[44:47], v[124:127], v[172:175], v[44:47]
	v_mfma_f32_16x16x32_bf16 v[40:43], v[136:139], v[172:175], v[40:43]
	v_mfma_f32_16x16x32_bf16 v[28:31], v[124:127], v[180:183], v[28:31]
	v_mfma_f32_16x16x32_bf16 v[24:27], v[136:139], v[180:183], v[24:27]
	v_mfma_f32_16x16x32_bf16 v[12:15], v[124:127], v[188:191], v[12:15]
	v_mfma_f32_16x16x32_bf16 v[8:11], v[136:139], v[188:191], v[8:11]
	v_mfma_f32_16x16x32_bf16 v[52:55], v[144:147], v[160:163], v[52:55]
	v_mfma_f32_16x16x32_bf16 v[48:51], v[152:155], v[160:163], v[48:51]
	v_mfma_f32_16x16x32_bf16 v[36:39], v[144:147], v[168:171], v[36:39]
	v_mfma_f32_16x16x32_bf16 v[32:35], v[152:155], v[168:171], v[32:35]
	v_mfma_f32_16x16x32_bf16 v[20:23], v[144:147], v[176:179], v[20:23]
	v_mfma_f32_16x16x32_bf16 v[16:19], v[152:155], v[176:179], v[16:19]
	v_mfma_f32_16x16x32_bf16 v[4:7], v[144:147], v[184:187], v[4:7]
	v_mfma_f32_16x16x32_bf16 v[0:3], v[152:155], v[184:187], v[0:3]
	v_mfma_f32_16x16x32_bf16 v[52:55], v[148:151], v[164:167], v[52:55]
	v_mfma_f32_16x16x32_bf16 v[48:51], v[156:159], v[164:167], v[48:51]
	v_mfma_f32_16x16x32_bf16 v[36:39], v[148:151], v[172:175], v[36:39]
	v_mfma_f32_16x16x32_bf16 v[32:35], v[156:159], v[172:175], v[32:35]
	v_mfma_f32_16x16x32_bf16 v[20:23], v[148:151], v[180:183], v[20:23]
	v_mfma_f32_16x16x32_bf16 v[16:19], v[156:159], v[180:183], v[16:19]
	v_mfma_f32_16x16x32_bf16 v[4:7], v[148:151], v[188:191], v[4:7]
	v_mfma_f32_16x16x32_bf16 v[0:3], v[156:159], v[188:191], v[0:3]
	s_barrier
	s_add_u32 vcc_lo, vcc_lo, 0x100
	s_addc_u32 vcc_hi, vcc_hi, 0
	s_add_u32 s82, s82, 0x100
	s_addc_u32 s83, s83, 0
	s_cmp_ge_u32 s2, s87
	s_mov_b32 s84, s2
	s_cbranch_scc0 .LBB0_724
	s_and_b64 vcc, exec, s[16:17]
	s_cbranch_vccz .LBB0_727
	s_barrier

; #define PG8_STAGE(bufoff, gbase, voff) do { _Pragma("unroll") for (int _i = 0; _i < 2; ++_i) \
;         __builtin_amdgcn_global_load_lds((const unsigned*)((const char*)(gbase) + (voff)[_i]), (PG8_LAS unsigned*)(lds + (bufoff) + ldsw + _i * 8192), 16, 0, 0); } while (0)
; #define PG8_LDA(dst, b, h) do { _Pragma("unroll") for (int m = 0; m < 4; ++m) _Pragma("unroll") for (int k = 0; k < 2; ++k) dst[m][k] = *(const PG8_LAS bf16x8*)(lds + PG8_SA(b, h) + aoff + m * 2048 + k * 1024); } while (0)
; #define PG8_LDB(dst, b, h) do { _Pragma("unroll") for (int n = 0; n < 2; ++n) _Pragma("unroll") for (int k = 0; k < 2; ++k) dst[n][k] = *(const PG8_LAS bf16x8*)(lds + PG8_SB(b, h) + boff + n * 2048 + k * 1024); } while (0)
; #define PG8_WAIT_V(n) asm volatile("s_waitcnt vmcnt(" #n ")" ::: "memory")
; #define PG8_WAIT_L(n) asm volatile("s_waitcnt lgkmcnt(" #n ")" ::: "memory")
; #define PG8_BAR __builtin_amdgcn_s_barrier()
; template <class Epi, class Sched, bool ALIGN_EPI = false, bool SP2 = false>
; __device__ __forceinline__ void gemm_phase(PG8_LAS unsigned char* lds, const Gemm g, const Sched& S, const Epi& E) {
;     ...
;         const bool has_next = S.next(ui + 1, nxt);
;         const char* nA = has_next ? (const char*)g.A + (size_t)nxt.pm * tstepA : cA; const char* nB = has_next ? (const char*)g.Bt + (size_t)nxt.pn * tstepB : cB;
;         for (int t = 0; t < nt; t += 2) {
;             const bool last = (t == nt - 2);
;             const char* a1 = cA + (size_t)(t + 1) * kstep;
;             const char* a2 = last ? nA : cA + (size_t)(t + 2) * kstep; const char* b2 = last ? nB : cB + (size_t)(t + 2) * kstep;
;             const char* a3 = a2 + kstep; const char* b3 = b2 + kstep;
;             if (last && has_next) S.a_ready(nxt);
;             if constexpr (SP2) {
;             PG8_LDB(B0, 0, 0); PG8_LDB(B1, 0, 1); PG8_SCHED; PG8_LDA(At, 0, 0); PG8_STAGE(PG8_SA(1, 1), a1 + hstepA, voffA);
;             PG8_WAIT_V(8); PG8_WAIT_L(0); PG8_BAR; PG8_MMA(0, 0, At, B0); PG8_MMA(0, 1, At, B1); PG8_BAR; PG8_SCHED;
;     ...
; #pragma unroll
;         for (int a = 0; a < 2; ++a)
; #pragma unroll
;             for (int b = 0; b < 2; ++b)
; #pragma unroll
;                 for (int m = 0; m < 4; ++m)
; #pragma unroll
;                     for (int n = 0; n < 2; ++n) acc[a][b][m][n] = (f32x4){0.f, 0.f, 0.f, 0.f};
;         cur = nxt; cA = nA; cB = nB; ++ui;
.LBB0_765:
	s_add_u32 s93, s82, 0x100
	v_mov_b32_e32 v0, 0
	s_addc_u32 s94, s83, 0
	s_mov_b32 s82, 0
	v_mov_b32_e32 v1, v0
	v_mov_b32_e32 v2, v0
	v_mov_b32_e32 v3, v0
	v_mov_b32_e32 v4, v0
	v_mov_b32_e32 v5, v0
	v_mov_b32_e32 v6, v0
	v_mov_b32_e32 v7, v0
	v_mov_b32_e32 v12, v0
	v_mov_b32_e32 v13, v0
	v_mov_b32_e32 v14, v0
	v_mov_b32_e32 v15, v0
	v_mov_b32_e32 v20, v0
	v_mov_b32_e32 v21, v0
	v_mov_b32_e32 v22, v0
	v_mov_b32_e32 v23, v0
	v_mov_b32_e32 v28, v0
	v_mov_b32_e32 v29, v0
	v_mov_b32_e32 v30, v0
	v_mov_b32_e32 v31, v0
	v_mov_b32_e32 v36, v0
	v_mov_b32_e32 v37, v0
	v_mov_b32_e32 v38, v0
	v_mov_b32_e32 v39, v0
	v_mov_b32_e32 v44, v0
	v_mov_b32_e32 v45, v0
	v_mov_b32_e32 v46, v0
	v_mov_b32_e32 v47, v0
	v_mov_b32_e32 v52, v0
	v_mov_b32_e32 v53, v0
	v_mov_b32_e32 v54, v0
	v_mov_b32_e32 v55, v0
	v_mov_b32_e32 v8, v0
	v_mov_b32_e32 v9, v0
	v_mov_b32_e32 v10, v0
	v_mov_b32_e32 v11, v0
	v_mov_b32_e32 v16, v0
	v_mov_b32_e32 v17, v0
	v_mov_b32_e32 v18, v0
	v_mov_b32_e32 v19, v0
	v_mov_b32_e32 v24, v0
	v_mov_b32_e32 v25, v0
	v_mov_b32_e32 v26, v0
	v_mov_b32_e32 v27, v0
	v_mov_b32_e32 v32, v0
	v_mov_b32_e32 v33, v0
	v_mov_b32_e32 v34, v0
	v_mov_b32_e32 v35, v0
	v_mov_b32_e32 v40, v0
	v_mov_b32_e32 v41, v0
	v_mov_b32_e32 v42, v0
	v_mov_b32_e32 v43, v0
	v_mov_b32_e32 v48, v0
	v_mov_b32_e32 v49, v0
	v_mov_b32_e32 v50, v0
	v_mov_b32_e32 v51, v0
	v_mov_b32_e32 v56, v0
	v_mov_b32_e32 v57, v0
	v_mov_b32_e32 v58, v0
	v_mov_b32_e32 v59, v0
	v_mov_b32_e32 v60, v0
	v_mov_b32_e32 v61, v0
	v_mov_b32_e32 v62, v0
	v_mov_b32_e32 v63, v0
	s_waitcnt vmcnt(0)
	v_mov_b32_e32 v64, v0
	v_mov_b32_e32 v65, v0
	v_mov_b32_e32 v66, v0
	v_mov_b32_e32 v67, v0
	v_mov_b32_e32 v68, v0
	v_mov_b32_e32 v69, v0
	v_mov_b32_e32 v70, v0
	v_mov_b32_e32 v71, v0
	v_mov_b32_e32 v76, v0
	v_mov_b32_e32 v77, v0
	v_mov_b32_e32 v78, v0
	v_mov_b32_e32 v79, v0
	v_mov_b32_e32 v84, v0
	v_mov_b32_e32 v85, v0
	v_mov_b32_e32 v86, v0
	v_mov_b32_e32 v87, v0
	v_mov_b32_e32 v92, v0
	v_mov_b32_e32 v93, v0
	v_mov_b32_e32 v94, v0
	v_mov_b32_e32 v95, v0
	v_mov_b32_e32 v100, v0
	v_mov_b32_e32 v101, v0
	v_mov_b32_e32 v102, v0
	v_mov_b32_e32 v103, v0
	v_mov_b32_e32 v108, v0
	v_mov_b32_e32 v109, v0
	v_mov_b32_e32 v110, v0
	v_mov_b32_e32 v111, v0
	v_mov_b32_e32 v116, v0
	v_mov_b32_e32 v117, v0
	v_mov_b32_e32 v118, v0
	v_mov_b32_e32 v119, v0
	v_mov_b32_e32 v72, v0
	v_mov_b32_e32 v73, v0
	v_mov_b32_e32 v74, v0
	v_mov_b32_e32 v75, v0
	v_mov_b32_e32 v80, v0
	v_mov_b32_e32 v81, v0
	v_mov_b32_e32 v82, v0
	v_mov_b32_e32 v83, v0
	v_mov_b32_e32 v88, v0
	v_mov_b32_e32 v89, v0
	v_mov_b32_e32 v90, v0
	v_mov_b32_e32 v91, v0
	v_mov_b32_e32 v96, v0
	v_mov_b32_e32 v97, v0
	v_mov_b32_e32 v98, v0
	v_mov_b32_e32 v99, v0
	v_mov_b32_e32 v104, v0
	v_mov_b32_e32 v105, v0
	v_mov_b32_e32 v106, v0
	v_mov_b32_e32 v107, v0
	v_mov_b32_e32 v112, v0
	v_mov_b32_e32 v113, v0
	v_mov_b32_e32 v114, v0
	v_mov_b32_e32 v115, v0
	v_mov_b32_e32 v120, v0
	v_mov_b32_e32 v121, v0
	v_mov_b32_e32 v122, v0
	v_mov_b32_e32 v123, v0
	v_mov_b32_e32 v124, v0
	v_mov_b32_e32 v125, v0
	v_mov_b32_e32 v126, v0
	v_mov_b32_e32 v127, v0
	s_cmp_lg_u64 s[10:11], 0
	s_cbranch_scc0 .Lprio_skip1
	s_setprio 1
.Lprio_skip1:
.LBB0_766:
	s_add_i32 s2, s82, 2
	s_add_u32 s4, s66, 0x100
	s_addc_u32 s5, s67, 0
	s_add_i32 s3, 0, 0x10000
	s_cmp_eq_u32 s88, s82
	s_cselect_b32 s83, s15, s5
	s_cselect_b32 s82, s14, s4
	s_cselect_b32 s97, s17, s94
	s_cselect_b32 s96, s16, s93
	s_add_i32 s30, 0, 0x14000
	v_add_u32_e32 v140, s3, v222
	v_add_u32_e32 v156, s30, v222
	ds_read_b128 v[128:131], v140
	ds_read_b128 v[132:135], v140 offset:1024
	ds_read_b128 v[136:139], v140 offset:2048
	ds_read_b128 v[140:143], v140 offset:3072
	ds_read_b128 v[144:147], v156
	ds_read_b128 v[148:151], v156 offset:1024
	ds_read_b128 v[152:155], v156 offset:2048
	ds_read_b128 v[156:159], v156 offset:3072
	s_add_i32 m0, s62, 0xc000
	ds_read_b128 v[160:163], v223
	ds_read_b128 v[164:167], v223 offset:1024
	ds_read_b128 v[168:171], v223 offset:2048
	ds_read_b128 v[172:175], v223 offset:3072
	ds_read_b128 v[176:179], v223 offset:4096
	ds_read_b128 v[180:183], v223 offset:5120
	ds_read_b128 v[184:187], v223 offset:6144
	ds_read_b128 v[188:191], v223 offset:7168
	global_load_lds_dwordx4 v206, s[66:67]
	s_add_i32 m0, s62, 0xe000
	s_nop 0
	global_load_lds_dwordx4 v204, s[66:67]
	s_waitcnt vmcnt(8)
	s_waitcnt lgkmcnt(0)
	s_barrier
	s_waitcnt lgkmcnt(0)
	v_mfma_f32_16x16x32_bf16 v[124:127], v[128:131], v[160:163], v[124:127]
	v_mfma_f32_16x16x32_bf16 v[120:123], v[136:139], v[160:163], v[120:123]
	v_mfma_f32_16x16x32_bf16 v[112:115], v[128:131], v[168:171], v[112:115]
	v_mfma_f32_16x16x32_bf16 v[104:107], v[136:139], v[168:171], v[104:107]
	v_mfma_f32_16x16x32_bf16 v[96:99], v[128:131], v[176:179], v[96:99]
	v_mfma_f32_16x16x32_bf16 v[88:91], v[136:139], v[176:179], v[88:91]
	v_mfma_f32_16x16x32_bf16 v[80:83], v[128:131], v[184:187], v[80:83]
	v_mfma_f32_16x16x32_bf16 v[72:75], v[136:139], v[184:187], v[72:75]
	v_mfma_f32_16x16x32_bf16 v[124:127], v[132:135], v[164:167], v[124:127]
	v_mfma_f32_16x16x32_bf16 v[120:123], v[140:143], v[164:167], v[120:123]
	v_mfma_f32_16x16x32_bf16 v[112:115], v[132:135], v[172:175], v[112:115]
	v_mfma_f32_16x16x32_bf16 v[104:107], v[140:143], v[172:175], v[104:107]
	v_mfma_f32_16x16x32_bf16 v[96:99], v[132:135], v[180:183], v[96:99]
	v_mfma_f32_16x16x32_bf16 v[88:91], v[140:143], v[180:183], v[88:91]
	v_mfma_f32_16x16x32_bf16 v[80:83], v[132:135], v[188:191], v[80:83]
	v_mfma_f32_16x16x32_bf16 v[72:75], v[140:143], v[188:191], v[72:75]
	v_mfma_f32_16x16x32_bf16 v[116:119], v[144:147], v[160:163], v[116:119]
	v_mfma_f32_16x16x32_bf16 v[108:111], v[152:155], v[160:163], v[108:111]
	v_mfma_f32_16x16x32_bf16 v[100:103], v[144:147], v[168:171], v[100:103]
	v_mfma_f32_16x16x32_bf16 v[92:95], v[152:155], v[168:171], v[92:95]
	v_mfma_f32_16x16x32_bf16 v[84:87], v[144:147], v[176:179], v[84:87]
	v_mfma_f32_16x16x32_bf16 v[76:79], v[152:155], v[176:179], v[76:79]
	v_mfma_f32_16x16x32_bf16 v[68:71], v[144:147], v[184:187], v[68:71]
	v_mfma_f32_16x16x32_bf16 v[64:67], v[152:155], v[184:187], v[64:67]
	v_mfma_f32_16x16x32_bf16 v[116:119], v[148:151], v[164:167], v[116:119]
	v_mfma_f32_16x16x32_bf16 v[108:111], v[156:159], v[164:167], v[108:111]
	v_mfma_f32_16x16x32_bf16 v[100:103], v[148:151], v[172:175], v[100:103]
	v_mfma_f32_16x16x32_bf16 v[92:95], v[156:159], v[172:175], v[92:95]
	v_mfma_f32_16x16x32_bf16 v[84:87], v[148:151], v[180:183], v[84:87]
	v_mfma_f32_16x16x32_bf16 v[76:79], v[156:159], v[180:183], v[76:79]
	v_mfma_f32_16x16x32_bf16 v[68:71], v[148:151], v[188:191], v[68:71]
	v_mfma_f32_16x16x32_bf16 v[64:67], v[156:159], v[188:191], v[64:67]
	s_barrier
; #define PG8_STAGE(bufoff, gbase, voff) do { _Pragma("unroll") for (int _i = 0; _i < 2; ++_i) \
;         __builtin_amdgcn_global_load_lds((const unsigned*)((const char*)(gbase) + (voff)[_i]), (PG8_LAS unsigned*)(lds + (bufoff) + ldsw + _i * 8192), 16, 0, 0); } while (0)
; #define PG8_LDA(dst, b, h) do { _Pragma("unroll") for (int m = 0; m < 4; ++m) _Pragma("unroll") for (int k = 0; k < 2; ++k) dst[m][k] = *(const PG8_LAS bf16x8*)(lds + PG8_SA(b, h) + aoff + m * 2048 + k * 1024); } while (0)
; #define PG8_LDB(dst, b, h) do { _Pragma("unroll") for (int n = 0; n < 2; ++n) _Pragma("unroll") for (int k = 0; k < 2; ++k) dst[n][k] = *(const PG8_LAS bf16x8*)(lds + PG8_SB(b, h) + boff + n * 2048 + k * 1024); } while (0)
; #define PG8_MMA(ai, bj, At, Bt) do { __builtin_amdgcn_s_setprio(1); _Pragma("unroll") for (int m = 0; m < 4; ++m) _Pragma("unroll") for (int n = 0; n < 2; ++n) _Pragma("unroll") for (int k = 0; k < 2; ++k) \
;         acc[ai][bj][m][n] = __builtin_amdgcn_mfma_f32_16x16x32_bf16(Bt[n][k], At[m][k], acc[ai][bj][m][n], 0, 0, 0); __builtin_amdgcn_s_setprio(0); } while (0)
; #define PG8_WAIT_V(n) asm volatile("s_waitcnt vmcnt(" #n ")" ::: "memory")
; #define PG8_WAIT_L(n) asm volatile("s_waitcnt lgkmcnt(" #n ")" ::: "memory")
; #define PG8_BAR __builtin_amdgcn_s_barrier()
; #define PG8_SCHED __builtin_amdgcn_sched_barrier(0)
; template <class Epi, class Sched, bool ALIGN_EPI = false, bool SP2 = false>
; __device__ __forceinline__ void gemm_phase(PG8_LAS unsigned char* lds, const Gemm g, const Sched& S, const Epi& E) {
;     ...
;             PG8_LDA(At, 0, 1); PG8_STAGE(PG8_SB(0, 0), b2, voffB); PG8_STAGE(PG8_SB(0, 1), b2 + hstepB, voffB); PG8_STAGE(PG8_SA(0, 0), a2, voffA);
;             PG8_WAIT_V(8); PG8_WAIT_L(0); PG8_BAR; PG8_MMA(1, 0, At, B0); PG8_MMA(1, 1, At, B1); PG8_BAR; PG8_SCHED;
;             PG8_LDB(B0, 1, 0); PG8_LDB(B1, 1, 1); PG8_SCHED; PG8_LDA(At, 1, 0); PG8_STAGE(PG8_SA(0, 1), a2 + hstepA, voffA);
	s_add_i32 s3, s3, s49
	s_mov_b32 m0, s3
	ds_read_b128 v[160:163], v223 offset:16384
	ds_read_b128 v[164:167], v223 offset:17408
	ds_read_b128 v[168:171], v223 offset:18432
	ds_read_b128 v[172:175], v223 offset:19456
	ds_read_b128 v[176:179], v223 offset:20480
	ds_read_b128 v[180:183], v223 offset:21504
	ds_read_b128 v[184:187], v223 offset:22528
	ds_read_b128 v[188:191], v223 offset:23552
	global_load_lds_dwordx4 v192, s[96:97]
	s_add_i32 m0, s3, 0x2000
	s_add_u32 s66, s96, s34
	s_addc_u32 s67, s97, 0
	s_add_i32 s3, s30, s49
	global_load_lds_dwordx4 v198, s[96:97]
	v_lshl_add_u64 v[212:213], s[66:67], 0, v[192:193]
	s_mov_b32 m0, s3
	v_lshl_add_u64 v[214:215], s[66:67], 0, v[198:199]
	global_load_lds_dwordx4 v192, s[66:67]
	s_add_i32 m0, s3, 0x2000
	s_nop 0
	global_load_lds_dwordx4 v198, s[66:67]
	s_mov_b32 m0, s62
	s_nop 0
	global_load_lds_dwordx4 v202, s[82:83]
	s_mov_b32 m0, s63
	s_nop 0
	global_load_lds_dwordx4 v200, s[82:83]
	s_waitcnt vmcnt(8)
	s_waitcnt lgkmcnt(0)
	s_barrier
	s_waitcnt lgkmcnt(0)
	v_mfma_f32_16x16x32_bf16 v[60:63], v[128:131], v[160:163], v[60:63]
	v_mfma_f32_16x16x32_bf16 v[56:59], v[136:139], v[160:163], v[56:59]
	v_mfma_f32_16x16x32_bf16 v[48:51], v[128:131], v[168:171], v[48:51]
	v_mfma_f32_16x16x32_bf16 v[40:43], v[136:139], v[168:171], v[40:43]
	v_mfma_f32_16x16x32_bf16 v[32:35], v[128:131], v[176:179], v[32:35]
	v_mfma_f32_16x16x32_bf16 v[24:27], v[136:139], v[176:179], v[24:27]
	v_mfma_f32_16x16x32_bf16 v[16:19], v[128:131], v[184:187], v[16:19]
	v_mfma_f32_16x16x32_bf16 v[8:11], v[136:139], v[184:187], v[8:11]
	v_mfma_f32_16x16x32_bf16 v[60:63], v[132:135], v[164:167], v[60:63]
	v_mfma_f32_16x16x32_bf16 v[56:59], v[140:143], v[164:167], v[56:59]
	v_mfma_f32_16x16x32_bf16 v[48:51], v[132:135], v[172:175], v[48:51]
	v_mfma_f32_16x16x32_bf16 v[40:43], v[140:143], v[172:175], v[40:43]
	v_mfma_f32_16x16x32_bf16 v[32:35], v[132:135], v[180:183], v[32:35]
	v_mfma_f32_16x16x32_bf16 v[24:27], v[140:143], v[180:183], v[24:27]
	v_mfma_f32_16x16x32_bf16 v[16:19], v[132:135], v[188:191], v[16:19]
	v_mfma_f32_16x16x32_bf16 v[8:11], v[140:143], v[188:191], v[8:11]
	v_mfma_f32_16x16x32_bf16 v[52:55], v[144:147], v[160:163], v[52:55]
	v_mfma_f32_16x16x32_bf16 v[44:47], v[152:155], v[160:163], v[44:47]
	v_mfma_f32_16x16x32_bf16 v[36:39], v[144:147], v[168:171], v[36:39]
	v_mfma_f32_16x16x32_bf16 v[28:31], v[152:155], v[168:171], v[28:31]
	v_mfma_f32_16x16x32_bf16 v[20:23], v[144:147], v[176:179], v[20:23]
	v_mfma_f32_16x16x32_bf16 v[12:15], v[152:155], v[176:179], v[12:15]
	v_mfma_f32_16x16x32_bf16 v[4:7], v[144:147], v[184:187], v[4:7]
	v_mfma_f32_16x16x32_bf16 v[0:3], v[152:155], v[184:187], v[0:3]
	v_mfma_f32_16x16x32_bf16 v[52:55], v[148:151], v[164:167], v[52:55]
	v_mfma_f32_16x16x32_bf16 v[44:47], v[156:159], v[164:167], v[44:47]
	v_mfma_f32_16x16x32_bf16 v[36:39], v[148:151], v[172:175], v[36:39]
	v_mfma_f32_16x16x32_bf16 v[28:31], v[156:159], v[172:175], v[28:31]
	v_mfma_f32_16x16x32_bf16 v[20:23], v[148:151], v[180:183], v[20:23]
	v_mfma_f32_16x16x32_bf16 v[12:15], v[156:159], v[180:183], v[12:15]
	v_mfma_f32_16x16x32_bf16 v[4:7], v[148:151], v[188:191], v[4:7]
	v_mfma_f32_16x16x32_bf16 v[0:3], v[156:159], v[188:191], v[0:3]
	s_barrier
	s_add_i32 s3, 0, 0x18000
	s_add_i32 s30, 0, 0x1c000
	v_add_u32_e32 v140, s3, v222
	v_add_u32_e32 v156, s30, v222
	ds_read_b128 v[128:131], v140
	ds_read_b128 v[132:135], v140 offset:1024
	ds_read_b128 v[136:139], v140 offset:2048
	ds_read_b128 v[140:143], v140 offset:3072
	ds_read_b128 v[144:147], v156
	ds_read_b128 v[148:151], v156 offset:1024
	ds_read_b128 v[152:155], v156 offset:2048
	ds_read_b128 v[156:159], v156 offset:3072
	s_add_u32 s66, s82, 0x130000
	s_addc_u32 s67, s83, 0
	s_mov_b32 m0, s64
	ds_read_b128 v[160:163], v223 offset:32768
	ds_read_b128 v[164:167], v223 offset:33792
	ds_read_b128 v[168:171], v223 offset:34816
	ds_read_b128 v[172:175], v223 offset:35840
	ds_read_b128 v[176:179], v223 offset:36864
	ds_read_b128 v[180:183], v223 offset:37888
	ds_read_b128 v[184:187], v223 offset:38912
	ds_read_b128 v[188:191], v223 offset:39936
	global_load_lds_dwordx4 v202, s[66:67]
	s_mov_b32 m0, s65
	s_nop 0
	global_load_lds_dwordx4 v200, s[66:67]
	s_waitcnt vmcnt(8)
	s_waitcnt lgkmcnt(0)
	s_barrier
; #define PG8_STAGE(bufoff, gbase, voff) do { _Pragma("unroll") for (int _i = 0; _i < 2; ++_i) \
;         __builtin_amdgcn_global_load_lds((const unsigned*)((const char*)(gbase) + (voff)[_i]), (PG8_LAS unsigned*)(lds + (bufoff) + ldsw + _i * 8192), 16, 0, 0); } while (0)
; #define PG8_LDA(dst, b, h) do { _Pragma("unroll") for (int m = 0; m < 4; ++m) _Pragma("unroll") for (int k = 0; k < 2; ++k) dst[m][k] = *(const PG8_LAS bf16x8*)(lds + PG8_SA(b, h) + aoff + m * 2048 + k * 1024); } while (0)
; #define PG8_MMA(ai, bj, At, Bt) do { __builtin_amdgcn_s_setprio(1); _Pragma("unroll") for (int m = 0; m < 4; ++m) _Pragma("unroll") for (int n = 0; n < 2; ++n) _Pragma("unroll") for (int k = 0; k < 2; ++k) \
;         acc[ai][bj][m][n] = __builtin_amdgcn_mfma_f32_16x16x32_bf16(Bt[n][k], At[m][k], acc[ai][bj][m][n], 0, 0, 0); __builtin_amdgcn_s_setprio(0); } while (0)
; #define PG8_WAIT_V(n) asm volatile("s_waitcnt vmcnt(" #n ")" ::: "memory")
; #define PG8_WAIT_L(n) asm volatile("s_waitcnt lgkmcnt(" #n ")" ::: "memory")
; #define PG8_BAR __builtin_amdgcn_s_barrier()
; #define PG8_SCHED __builtin_amdgcn_sched_barrier(0)
; template <class Epi, class Sched, bool ALIGN_EPI = false, bool SP2 = false>
; __device__ __forceinline__ void gemm_phase(PG8_LAS unsigned char* lds, const Gemm g, const Sched& S, const Epi& E) {
;     ...
;             PG8_WAIT_V(8); PG8_WAIT_L(0); PG8_BAR; PG8_MMA(0, 0, At, B0); PG8_MMA(0, 1, At, B1); PG8_BAR; PG8_SCHED;
;             PG8_LDA(At, 1, 1); PG8_STAGE(PG8_SB(1, 0), b3, voffB); PG8_STAGE(PG8_SB(1, 1), b3 + hstepB, voffB); PG8_STAGE(PG8_SA(1, 0), a3, voffA);
;             PG8_WAIT_V(8); PG8_WAIT_L(0); PG8_BAR; PG8_MMA(1, 0, At, B0); PG8_MMA(1, 1, At, B1); PG8_BAR; PG8_SCHED;
;     ...
;         if constexpr (ALIGN_EPI) { if (wr == 0) PG8_BAR; }
	s_waitcnt lgkmcnt(0)
	v_mfma_f32_16x16x32_bf16 v[124:127], v[128:131], v[160:163], v[124:127]
	v_mfma_f32_16x16x32_bf16 v[120:123], v[136:139], v[160:163], v[120:123]
	v_mfma_f32_16x16x32_bf16 v[112:115], v[128:131], v[168:171], v[112:115]
	v_mfma_f32_16x16x32_bf16 v[104:107], v[136:139], v[168:171], v[104:107]
	v_mfma_f32_16x16x32_bf16 v[96:99], v[128:131], v[176:179], v[96:99]
	v_mfma_f32_16x16x32_bf16 v[88:91], v[136:139], v[176:179], v[88:91]
	v_mfma_f32_16x16x32_bf16 v[80:83], v[128:131], v[184:187], v[80:83]
	v_mfma_f32_16x16x32_bf16 v[72:75], v[136:139], v[184:187], v[72:75]
	v_mfma_f32_16x16x32_bf16 v[124:127], v[132:135], v[164:167], v[124:127]
	v_mfma_f32_16x16x32_bf16 v[120:123], v[140:143], v[164:167], v[120:123]
	v_mfma_f32_16x16x32_bf16 v[112:115], v[132:135], v[172:175], v[112:115]
	v_mfma_f32_16x16x32_bf16 v[104:107], v[140:143], v[172:175], v[104:107]
	v_mfma_f32_16x16x32_bf16 v[96:99], v[132:135], v[180:183], v[96:99]
	v_mfma_f32_16x16x32_bf16 v[88:91], v[140:143], v[180:183], v[88:91]
	v_mfma_f32_16x16x32_bf16 v[80:83], v[132:135], v[188:191], v[80:83]
	v_mfma_f32_16x16x32_bf16 v[72:75], v[140:143], v[188:191], v[72:75]
	v_mfma_f32_16x16x32_bf16 v[116:119], v[144:147], v[160:163], v[116:119]
	v_mfma_f32_16x16x32_bf16 v[108:111], v[152:155], v[160:163], v[108:111]
	v_mfma_f32_16x16x32_bf16 v[100:103], v[144:147], v[168:171], v[100:103]
	v_mfma_f32_16x16x32_bf16 v[92:95], v[152:155], v[168:171], v[92:95]
	v_mfma_f32_16x16x32_bf16 v[84:87], v[144:147], v[176:179], v[84:87]
	v_mfma_f32_16x16x32_bf16 v[76:79], v[152:155], v[176:179], v[76:79]
	v_mfma_f32_16x16x32_bf16 v[68:71], v[144:147], v[184:187], v[68:71]
	v_mfma_f32_16x16x32_bf16 v[64:67], v[152:155], v[184:187], v[64:67]
	v_mfma_f32_16x16x32_bf16 v[116:119], v[148:151], v[164:167], v[116:119]
	v_mfma_f32_16x16x32_bf16 v[108:111], v[156:159], v[164:167], v[108:111]
	v_mfma_f32_16x16x32_bf16 v[100:103], v[148:151], v[172:175], v[100:103]
	v_mfma_f32_16x16x32_bf16 v[92:95], v[156:159], v[172:175], v[92:95]
	v_mfma_f32_16x16x32_bf16 v[84:87], v[148:151], v[180:183], v[84:87]
	v_mfma_f32_16x16x32_bf16 v[76:79], v[156:159], v[180:183], v[76:79]
	v_mfma_f32_16x16x32_bf16 v[68:71], v[148:151], v[188:191], v[68:71]
	v_mfma_f32_16x16x32_bf16 v[64:67], v[156:159], v[188:191], v[64:67]
	s_barrier
	s_add_i32 s3, s3, s49
	s_add_i32 m0, s3, 0xffffff80
	ds_read_b128 v[160:163], v223 offset:49152
	ds_read_b128 v[164:167], v223 offset:50176
	ds_read_b128 v[168:171], v223 offset:51200
	ds_read_b128 v[172:175], v223 offset:52224
	ds_read_b128 v[176:179], v223 offset:53248
	ds_read_b128 v[180:183], v223 offset:54272
	ds_read_b128 v[184:187], v223 offset:55296
	ds_read_b128 v[188:191], v223 offset:56320
	global_load_lds_dwordx4 v192, s[96:97] offset:128
	s_add_i32 m0, s3, 0x1f80
	s_add_i32 s3, s30, s49
	global_load_lds_dwordx4 v198, s[96:97] offset:128
	v_lshl_add_u64 v[208:209], v[212:213], 0, s[36:37]
	s_mov_b32 m0, s3
	s_nop 0
	global_load_lds_dwordx4 v[208:209], off
	v_lshl_add_u64 v[208:209], v[214:215], 0, s[36:37]
	s_add_i32 m0, s3, 0x2000
	s_nop 0
	global_load_lds_dwordx4 v[208:209], off
	s_add_i32 m0, s86, 0xffffff80
	s_nop 0
	global_load_lds_dwordx4 v202, s[82:83] offset:128
	s_add_i32 m0, s87, 0xffffff80
	s_nop 0
	global_load_lds_dwordx4 v200, s[82:83] offset:128
	s_waitcnt vmcnt(8)
	s_waitcnt lgkmcnt(0)
	s_barrier
	s_waitcnt lgkmcnt(0)
	v_mfma_f32_16x16x32_bf16 v[60:63], v[128:131], v[160:163], v[60:63]
	v_mfma_f32_16x16x32_bf16 v[56:59], v[136:139], v[160:163], v[56:59]
	v_mfma_f32_16x16x32_bf16 v[48:51], v[128:131], v[168:171], v[48:51]
	v_mfma_f32_16x16x32_bf16 v[40:43], v[136:139], v[168:171], v[40:43]
	v_mfma_f32_16x16x32_bf16 v[32:35], v[128:131], v[176:179], v[32:35]
	v_mfma_f32_16x16x32_bf16 v[24:27], v[136:139], v[176:179], v[24:27]
	v_mfma_f32_16x16x32_bf16 v[16:19], v[128:131], v[184:187], v[16:19]
	v_mfma_f32_16x16x32_bf16 v[8:11], v[136:139], v[184:187], v[8:11]
	v_mfma_f32_16x16x32_bf16 v[60:63], v[132:135], v[164:167], v[60:63]
	v_mfma_f32_16x16x32_bf16 v[56:59], v[140:143], v[164:167], v[56:59]
	v_mfma_f32_16x16x32_bf16 v[48:51], v[132:135], v[172:175], v[48:51]
	v_mfma_f32_16x16x32_bf16 v[40:43], v[140:143], v[172:175], v[40:43]
	v_mfma_f32_16x16x32_bf16 v[32:35], v[132:135], v[180:183], v[32:35]
	v_mfma_f32_16x16x32_bf16 v[24:27], v[140:143], v[180:183], v[24:27]
	v_mfma_f32_16x16x32_bf16 v[16:19], v[132:135], v[188:191], v[16:19]
	v_mfma_f32_16x16x32_bf16 v[8:11], v[140:143], v[188:191], v[8:11]
	v_mfma_f32_16x16x32_bf16 v[52:55], v[144:147], v[160:163], v[52:55]
	v_mfma_f32_16x16x32_bf16 v[44:47], v[152:155], v[160:163], v[44:47]
	v_mfma_f32_16x16x32_bf16 v[36:39], v[144:147], v[168:171], v[36:39]
	v_mfma_f32_16x16x32_bf16 v[28:31], v[152:155], v[168:171], v[28:31]
	v_mfma_f32_16x16x32_bf16 v[20:23], v[144:147], v[176:179], v[20:23]
	v_mfma_f32_16x16x32_bf16 v[12:15], v[152:155], v[176:179], v[12:15]
	v_mfma_f32_16x16x32_bf16 v[4:7], v[144:147], v[184:187], v[4:7]
	v_mfma_f32_16x16x32_bf16 v[0:3], v[152:155], v[184:187], v[0:3]
	v_mfma_f32_16x16x32_bf16 v[52:55], v[148:151], v[164:167], v[52:55]
	v_mfma_f32_16x16x32_bf16 v[44:47], v[156:159], v[164:167], v[44:47]
	v_mfma_f32_16x16x32_bf16 v[36:39], v[148:151], v[172:175], v[36:39]
	v_mfma_f32_16x16x32_bf16 v[28:31], v[156:159], v[172:175], v[28:31]
	v_mfma_f32_16x16x32_bf16 v[20:23], v[148:151], v[180:183], v[20:23]
	v_mfma_f32_16x16x32_bf16 v[12:15], v[156:159], v[180:183], v[12:15]
	v_mfma_f32_16x16x32_bf16 v[4:7], v[148:151], v[188:191], v[4:7]
	v_mfma_f32_16x16x32_bf16 v[0:3], v[156:159], v[188:191], v[0:3]
	s_barrier
	s_add_u32 s93, s93, 0x100
	s_addc_u32 s94, s94, 0
	s_cmp_ge_u32 s2, s80
	s_mov_b64 s[66:67], s[4:5]
	s_mov_b32 s82, s2
	s_cbranch_scc0 .LBB0_766
	s_and_b64 vcc, exec, s[12:13]
	s_cbranch_vccz .LBB0_769
	s_barrier

; #define PG8_STAGE(bufoff, gbase, voff) do { _Pragma("unroll") for (int _i = 0; _i < 2; ++_i) \
;         __builtin_amdgcn_global_load_lds((const unsigned*)((const char*)(gbase) + (voff)[_i]), (PG8_LAS unsigned*)(lds + (bufoff) + ldsw + _i * 8192), 16, 0, 0); } while (0)
; #define PG8_LDA(dst, b, h) do { _Pragma("unroll") for (int m = 0; m < 4; ++m) _Pragma("unroll") for (int k = 0; k < 2; ++k) dst[m][k] = *(const PG8_LAS bf16x8*)(lds + PG8_SA(b, h) + aoff + m * 2048 + k * 1024); } while (0)
; #define PG8_LDB(dst, b, h) do { _Pragma("unroll") for (int n = 0; n < 2; ++n) _Pragma("unroll") for (int k = 0; k < 2; ++k) dst[n][k] = *(const PG8_LAS bf16x8*)(lds + PG8_SB(b, h) + boff + n * 2048 + k * 1024); } while (0)
; #define PG8_SCHED __builtin_amdgcn_sched_barrier(0)
; template <class Epi, class Sched, bool ALIGN_EPI = false, bool SP2 = false>
; __device__ __forceinline__ void gemm_phase(PG8_LAS unsigned char* lds, const Gemm g, const Sched& S, const Epi& E) {
;     ...
;         const bool has_next = S.next(ui + 1, nxt);
;         const char* nA = has_next ? (const char*)g.A + (size_t)nxt.pm * tstepA : cA; const char* nB = has_next ? (const char*)g.Bt + (size_t)nxt.pn * tstepB : cB;
;         for (int t = 0; t < nt; t += 2) {
;             const bool last = (t == nt - 2);
;             const char* a1 = cA + (size_t)(t + 1) * kstep;
;             const char* a2 = last ? nA : cA + (size_t)(t + 2) * kstep; const char* b2 = last ? nB : cB + (size_t)(t + 2) * kstep;
;             const char* a3 = a2 + kstep; const char* b3 = b2 + kstep;
;             if (last && has_next) S.a_ready(nxt);
;             if constexpr (SP2) {
;             PG8_LDB(B0, 0, 0); PG8_LDB(B1, 0, 1); PG8_SCHED; PG8_LDA(At, 0, 0); PG8_STAGE(PG8_SA(1, 1), a1 + hstepA, voffA);
;     ...
; #pragma unroll
;         for (int a = 0; a < 2; ++a)
; #pragma unroll
;             for (int b = 0; b < 2; ++b)
; #pragma unroll
;                 for (int m = 0; m < 4; ++m)
; #pragma unroll
;                     for (int n = 0; n < 2; ++n) acc[a][b][m][n] = (f32x4){0.f, 0.f, 0.f, 0.f};
.LBB0_816:
	s_ashr_i32 s91, s90, 31
	s_lshl_b64 s[2:3], s[90:91], 19
	s_add_u32 s82, s24, s2
	s_addc_u32 s83, s25, s3
	s_and_b64 s[2:3], s[4:5], exec
	s_cselect_b32 s7, s83, s9
	s_cselect_b32 s12, s82, s8
	s_ashr_i32 s89, s88, 31
	s_lshl_b64 s[2:3], s[88:89], 19
	s_add_u32 s92, s34, s2
	s_addc_u32 s93, s80, s3
	s_and_b64 s[2:3], s[4:5], exec
	s_cselect_b32 s13, s93, s1
	s_cselect_b32 s15, s92, s0
	s_add_u32 s16, s0, 0x100
	s_addc_u32 s17, s1, 0
	s_add_u32 s0, s8, 0x40080
	v_mov_b32_e32 v0, 0
	s_addc_u32 s1, s9, 0
	s_mov_b32 s78, -2
	v_mov_b32_e32 v1, v0
	v_mov_b32_e32 v2, v0
	v_mov_b32_e32 v3, v0
	v_mov_b32_e32 v4, v0
	v_mov_b32_e32 v5, v0
	v_mov_b32_e32 v6, v0
	v_mov_b32_e32 v7, v0
	v_mov_b32_e32 v16, v0
	v_mov_b32_e32 v17, v0
	v_mov_b32_e32 v18, v0
	v_mov_b32_e32 v19, v0
	v_mov_b32_e32 v20, v0
	v_mov_b32_e32 v21, v0
	v_mov_b32_e32 v22, v0
	v_mov_b32_e32 v23, v0
	v_mov_b32_e32 v32, v0
	v_mov_b32_e32 v33, v0
	v_mov_b32_e32 v34, v0
	v_mov_b32_e32 v35, v0
	v_mov_b32_e32 v36, v0
	v_mov_b32_e32 v37, v0
	v_mov_b32_e32 v38, v0
	v_mov_b32_e32 v39, v0
	v_mov_b32_e32 v48, v0
	v_mov_b32_e32 v49, v0
	v_mov_b32_e32 v50, v0
	v_mov_b32_e32 v51, v0
	v_mov_b32_e32 v52, v0
	v_mov_b32_e32 v53, v0
	v_mov_b32_e32 v54, v0
	v_mov_b32_e32 v55, v0
	v_mov_b32_e32 v8, v0
	v_mov_b32_e32 v9, v0
	v_mov_b32_e32 v10, v0
	v_mov_b32_e32 v11, v0
	v_mov_b32_e32 v12, v0
	v_mov_b32_e32 v13, v0
	v_mov_b32_e32 v14, v0
	v_mov_b32_e32 v15, v0
	v_mov_b32_e32 v24, v0
	v_mov_b32_e32 v25, v0
	v_mov_b32_e32 v26, v0
	v_mov_b32_e32 v27, v0
	v_mov_b32_e32 v28, v0
	v_mov_b32_e32 v29, v0
	v_mov_b32_e32 v30, v0
	v_mov_b32_e32 v31, v0
	v_mov_b32_e32 v40, v0
	v_mov_b32_e32 v41, v0
	v_mov_b32_e32 v42, v0
	v_mov_b32_e32 v43, v0
	v_mov_b32_e32 v44, v0
	v_mov_b32_e32 v45, v0
	v_mov_b32_e32 v46, v0
	v_mov_b32_e32 v47, v0
	v_mov_b32_e32 v56, v0
	v_mov_b32_e32 v57, v0
	v_mov_b32_e32 v58, v0
	v_mov_b32_e32 v59, v0
	v_mov_b32_e32 v60, v0
	v_mov_b32_e32 v61, v0
	v_mov_b32_e32 v62, v0
	v_mov_b32_e32 v63, v0
	s_waitcnt vmcnt(0)
	v_mov_b32_e32 v64, v0
	v_mov_b32_e32 v65, v0
	v_mov_b32_e32 v66, v0
	v_mov_b32_e32 v67, v0
	v_mov_b32_e32 v68, v0
	v_mov_b32_e32 v69, v0
	v_mov_b32_e32 v70, v0
	v_mov_b32_e32 v71, v0
	v_mov_b32_e32 v96, v0
	v_mov_b32_e32 v97, v0
	v_mov_b32_e32 v98, v0
	v_mov_b32_e32 v99, v0
	v_mov_b32_e32 v100, v0
	v_mov_b32_e32 v101, v0
	v_mov_b32_e32 v102, v0
	v_mov_b32_e32 v103, v0
	v_mov_b32_e32 v128, v0
	v_mov_b32_e32 v129, v0
	v_mov_b32_e32 v130, v0
	v_mov_b32_e32 v131, v0
	v_mov_b32_e32 v132, v0
	v_mov_b32_e32 v133, v0
	v_mov_b32_e32 v134, v0
	v_mov_b32_e32 v135, v0
	v_mov_b32_e32 v160, v0
	v_mov_b32_e32 v161, v0
	v_mov_b32_e32 v162, v0
	v_mov_b32_e32 v163, v0
	v_mov_b32_e32 v164, v0
	v_mov_b32_e32 v165, v0
	v_mov_b32_e32 v166, v0
	v_mov_b32_e32 v167, v0
	v_mov_b32_e32 v88, v0
	v_mov_b32_e32 v89, v0
	v_mov_b32_e32 v90, v0
	v_mov_b32_e32 v91, v0
	v_mov_b32_e32 v92, v0
	v_mov_b32_e32 v93, v0
	v_mov_b32_e32 v94, v0
	v_mov_b32_e32 v95, v0
	v_mov_b32_e32 v120, v0
	v_mov_b32_e32 v121, v0
	v_mov_b32_e32 v122, v0
	v_mov_b32_e32 v123, v0
	v_mov_b32_e32 v124, v0
	v_mov_b32_e32 v125, v0
	v_mov_b32_e32 v126, v0
	v_mov_b32_e32 v127, v0
	v_mov_b32_e32 v152, v0
	v_mov_b32_e32 v153, v0
	v_mov_b32_e32 v154, v0
	v_mov_b32_e32 v155, v0
	v_mov_b32_e32 v156, v0
	v_mov_b32_e32 v157, v0
	v_mov_b32_e32 v158, v0
	v_mov_b32_e32 v159, v0
	v_mov_b32_e32 v184, v0
	v_mov_b32_e32 v185, v0
	v_mov_b32_e32 v186, v0
	v_mov_b32_e32 v187, v0
	v_mov_b32_e32 v188, v0
	v_mov_b32_e32 v189, v0
	v_mov_b32_e32 v190, v0
	v_mov_b32_e32 v191, v0
	s_cmp_lg_u64 s[86:87], 0
	s_cbranch_scc0 .Lprio_skip0
	s_setprio 1
.Lprio_skip0:
.LBB0_817:
	s_add_u32 s2, s0, 0xfffc0080
	s_addc_u32 s3, s1, -1
	s_add_i32 s30, 0, 0x10000
	s_cmp_eq_u32 s78, 12
	s_cselect_b32 s11, s7, s3
	s_cselect_b32 s10, s12, s2
	s_cselect_b32 s9, s13, s17
	s_cselect_b32 s8, s15, s16
	s_add_i32 s31, 0, 0x14000
	v_add_u32_e32 v84, s30, v240
	v_add_u32_e32 v116, s31, v240
	ds_read_b128 v[72:75], v84
	ds_read_b128 v[76:79], v84 offset:1024
	ds_read_b128 v[80:83], v84 offset:2048
	ds_read_b128 v[84:87], v84 offset:3072
	ds_read_b128 v[104:107], v116
	ds_read_b128 v[108:111], v116 offset:1024
	ds_read_b128 v[112:115], v116 offset:2048
	ds_read_b128 v[116:119], v116 offset:3072
	s_add_i32 m0, s19, 0xc000
	ds_read_b128 v[136:139], v241
	ds_read_b128 v[140:143], v241 offset:1024
	ds_read_b128 v[144:147], v241 offset:2048
	ds_read_b128 v[148:151], v241 offset:3072
	ds_read_b128 v[168:171], v241 offset:4096
	ds_read_b128 v[172:175], v241 offset:5120
	ds_read_b128 v[176:179], v241 offset:6144
	ds_read_b128 v[180:183], v241 offset:7168
	global_load_lds_dwordx4 v206, s[0:1]
	s_add_i32 m0, s19, 0xe000
	s_nop 0
	global_load_lds_dwordx4 v204, s[0:1]
	s_waitcnt vmcnt(8)
	s_waitcnt lgkmcnt(0)
	s_barrier
; #define PG8_STAGE(bufoff, gbase, voff) do { _Pragma("unroll") for (int _i = 0; _i < 2; ++_i) \
;         __builtin_amdgcn_global_load_lds((const unsigned*)((const char*)(gbase) + (voff)[_i]), (PG8_LAS unsigned*)(lds + (bufoff) + ldsw + _i * 8192), 16, 0, 0); } while (0)
; #define PG8_LDA(dst, b, h) do { _Pragma("unroll") for (int m = 0; m < 4; ++m) _Pragma("unroll") for (int k = 0; k < 2; ++k) dst[m][k] = *(const PG8_LAS bf16x8*)(lds + PG8_SA(b, h) + aoff + m * 2048 + k * 1024); } while (0)
; #define PG8_MMA(ai, bj, At, Bt) do { __builtin_amdgcn_s_setprio(1); _Pragma("unroll") for (int m = 0; m < 4; ++m) _Pragma("unroll") for (int n = 0; n < 2; ++n) _Pragma("unroll") for (int k = 0; k < 2; ++k) \
;         acc[ai][bj][m][n] = __builtin_amdgcn_mfma_f32_16x16x32_bf16(Bt[n][k], At[m][k], acc[ai][bj][m][n], 0, 0, 0); __builtin_amdgcn_s_setprio(0); } while (0)
; #define PG8_WAIT_V(n) asm volatile("s_waitcnt vmcnt(" #n ")" ::: "memory")
; #define PG8_WAIT_L(n) asm volatile("s_waitcnt lgkmcnt(" #n ")" ::: "memory")
; #define PG8_BAR __builtin_amdgcn_s_barrier()
; #define PG8_SCHED __builtin_amdgcn_sched_barrier(0)
; template <class Epi, class Sched, bool ALIGN_EPI = false, bool SP2 = false>
; __device__ __forceinline__ void gemm_phase(PG8_LAS unsigned char* lds, const Gemm g, const Sched& S, const Epi& E) {
;     ...
;             PG8_WAIT_V(8); PG8_WAIT_L(0); PG8_BAR; PG8_MMA(0, 0, At, B0); PG8_MMA(0, 1, At, B1); PG8_BAR; PG8_SCHED;
;             PG8_LDA(At, 0, 1); PG8_STAGE(PG8_SB(0, 0), b2, voffB); PG8_STAGE(PG8_SB(0, 1), b2 + hstepB, voffB); PG8_STAGE(PG8_SA(0, 0), a2, voffA);
;             PG8_WAIT_V(8); PG8_WAIT_L(0); PG8_BAR; PG8_MMA(1, 0, At, B0); PG8_MMA(1, 1, At, B1); PG8_BAR; PG8_SCHED;
	s_waitcnt lgkmcnt(0)
	v_mfma_f32_16x16x32_bf16 v[188:191], v[72:75], v[136:139], v[188:191]
	v_mfma_f32_16x16x32_bf16 v[184:187], v[80:83], v[136:139], v[184:187]
	v_mfma_f32_16x16x32_bf16 v[156:159], v[72:75], v[144:147], v[156:159]
	v_mfma_f32_16x16x32_bf16 v[152:155], v[80:83], v[144:147], v[152:155]
	v_mfma_f32_16x16x32_bf16 v[124:127], v[72:75], v[168:171], v[124:127]
	v_mfma_f32_16x16x32_bf16 v[120:123], v[80:83], v[168:171], v[120:123]
	v_mfma_f32_16x16x32_bf16 v[92:95], v[72:75], v[176:179], v[92:95]
	v_mfma_f32_16x16x32_bf16 v[88:91], v[80:83], v[176:179], v[88:91]
	v_mfma_f32_16x16x32_bf16 v[188:191], v[76:79], v[140:143], v[188:191]
	v_mfma_f32_16x16x32_bf16 v[184:187], v[84:87], v[140:143], v[184:187]
	v_mfma_f32_16x16x32_bf16 v[156:159], v[76:79], v[148:151], v[156:159]
	v_mfma_f32_16x16x32_bf16 v[152:155], v[84:87], v[148:151], v[152:155]
	v_mfma_f32_16x16x32_bf16 v[124:127], v[76:79], v[172:175], v[124:127]
	v_mfma_f32_16x16x32_bf16 v[120:123], v[84:87], v[172:175], v[120:123]
	v_mfma_f32_16x16x32_bf16 v[92:95], v[76:79], v[180:183], v[92:95]
	v_mfma_f32_16x16x32_bf16 v[88:91], v[84:87], v[180:183], v[88:91]
	v_mfma_f32_16x16x32_bf16 v[164:167], v[104:107], v[136:139], v[164:167]
	v_mfma_f32_16x16x32_bf16 v[132:135], v[104:107], v[144:147], v[132:135]
	v_mfma_f32_16x16x32_bf16 v[128:131], v[112:115], v[144:147], v[128:131]
	v_mfma_f32_16x16x32_bf16 v[100:103], v[104:107], v[168:171], v[100:103]
	v_mfma_f32_16x16x32_bf16 v[96:99], v[112:115], v[168:171], v[96:99]
	v_mfma_f32_16x16x32_bf16 v[68:71], v[104:107], v[176:179], v[68:71]
	v_mfma_f32_16x16x32_bf16 v[64:67], v[112:115], v[176:179], v[64:67]
	v_mfma_f32_16x16x32_bf16 v[164:167], v[108:111], v[140:143], v[164:167]
	v_mfma_f32_16x16x32_bf16 v[136:139], v[112:115], v[136:139], v[160:163]
	v_mfma_f32_16x16x32_bf16 v[132:135], v[108:111], v[148:151], v[132:135]
	v_mfma_f32_16x16x32_bf16 v[128:131], v[116:119], v[148:151], v[128:131]
	v_mfma_f32_16x16x32_bf16 v[100:103], v[108:111], v[172:175], v[100:103]
	v_mfma_f32_16x16x32_bf16 v[96:99], v[116:119], v[172:175], v[96:99]
	v_mfma_f32_16x16x32_bf16 v[68:71], v[108:111], v[180:183], v[68:71]
	v_mfma_f32_16x16x32_bf16 v[64:67], v[116:119], v[180:183], v[64:67]
	v_mfma_f32_16x16x32_bf16 v[136:139], v[116:119], v[140:143], v[136:139]
	s_barrier
	s_add_i32 s2, s30, s18
	s_mov_b32 m0, s2
	ds_read_b128 v[140:143], v241 offset:16384
	ds_read_b128 v[144:147], v241 offset:17408
	ds_read_b128 v[148:151], v241 offset:18432
	ds_read_b128 v[160:163], v241 offset:19456
	ds_read_b128 v[168:171], v241 offset:20480
	ds_read_b128 v[172:175], v241 offset:21504
	ds_read_b128 v[176:179], v241 offset:22528
	ds_read_b128 v[180:183], v241 offset:23552
	global_load_lds_dwordx4 v192, s[8:9]
	s_add_i32 m0, s2, 0x2000
	s_add_u32 s2, s8, 0x40000
	s_addc_u32 s3, s9, 0
	s_add_i32 s30, s31, s18
	global_load_lds_dwordx4 v202, s[8:9]
	s_mov_b32 m0, s30
	s_nop 0
	global_load_lds_dwordx4 v192, s[2:3]
	s_add_i32 m0, s30, 0x2000
	s_nop 0
	global_load_lds_dwordx4 v202, s[2:3]
	s_mov_b32 m0, s19
	s_nop 0
	global_load_lds_dwordx4 v198, s[10:11]
	s_mov_b32 m0, s45
	s_nop 0
	global_load_lds_dwordx4 v200, s[10:11]
	s_waitcnt vmcnt(8)
	s_waitcnt lgkmcnt(0)
	s_barrier
	s_waitcnt lgkmcnt(0)
	v_mfma_f32_16x16x32_bf16 v[60:63], v[72:75], v[140:143], v[60:63]
	v_mfma_f32_16x16x32_bf16 v[56:59], v[80:83], v[140:143], v[56:59]
	v_mfma_f32_16x16x32_bf16 v[44:47], v[72:75], v[148:151], v[44:47]
	v_mfma_f32_16x16x32_bf16 v[40:43], v[80:83], v[148:151], v[40:43]
	v_mfma_f32_16x16x32_bf16 v[28:31], v[72:75], v[168:171], v[28:31]
	v_mfma_f32_16x16x32_bf16 v[24:27], v[80:83], v[168:171], v[24:27]
	v_mfma_f32_16x16x32_bf16 v[12:15], v[72:75], v[176:179], v[12:15]
	v_mfma_f32_16x16x32_bf16 v[8:11], v[80:83], v[176:179], v[8:11]
	v_mfma_f32_16x16x32_bf16 v[60:63], v[76:79], v[144:147], v[60:63]
	v_mfma_f32_16x16x32_bf16 v[56:59], v[84:87], v[144:147], v[56:59]
	v_mfma_f32_16x16x32_bf16 v[44:47], v[76:79], v[160:163], v[44:47]
	v_mfma_f32_16x16x32_bf16 v[40:43], v[84:87], v[160:163], v[40:43]
	v_mfma_f32_16x16x32_bf16 v[28:31], v[76:79], v[172:175], v[28:31]
	v_mfma_f32_16x16x32_bf16 v[24:27], v[84:87], v[172:175], v[24:27]
	v_mfma_f32_16x16x32_bf16 v[12:15], v[76:79], v[180:183], v[12:15]
	v_mfma_f32_16x16x32_bf16 v[8:11], v[84:87], v[180:183], v[8:11]
	v_mfma_f32_16x16x32_bf16 v[52:55], v[104:107], v[140:143], v[52:55]
	v_mfma_f32_16x16x32_bf16 v[48:51], v[112:115], v[140:143], v[48:51]
	v_mfma_f32_16x16x32_bf16 v[36:39], v[104:107], v[148:151], v[36:39]
	v_mfma_f32_16x16x32_bf16 v[32:35], v[112:115], v[148:151], v[32:35]
	v_mfma_f32_16x16x32_bf16 v[20:23], v[104:107], v[168:171], v[20:23]
	v_mfma_f32_16x16x32_bf16 v[16:19], v[112:115], v[168:171], v[16:19]
	v_mfma_f32_16x16x32_bf16 v[4:7], v[104:107], v[176:179], v[4:7]
	v_mfma_f32_16x16x32_bf16 v[0:3], v[112:115], v[176:179], v[0:3]
	v_mfma_f32_16x16x32_bf16 v[52:55], v[108:111], v[144:147], v[52:55]
	v_mfma_f32_16x16x32_bf16 v[48:51], v[116:119], v[144:147], v[48:51]
	v_mfma_f32_16x16x32_bf16 v[36:39], v[108:111], v[160:163], v[36:39]
	v_mfma_f32_16x16x32_bf16 v[32:35], v[116:119], v[160:163], v[32:35]
	v_mfma_f32_16x16x32_bf16 v[20:23], v[108:111], v[172:175], v[20:23]
	v_mfma_f32_16x16x32_bf16 v[16:19], v[116:119], v[172:175], v[16:19]
	v_mfma_f32_16x16x32_bf16 v[4:7], v[108:111], v[180:183], v[4:7]
	v_mfma_f32_16x16x32_bf16 v[0:3], v[116:119], v[180:183], v[0:3]
	s_barrier
; #define PG8_STAGE(bufoff, gbase, voff) do { _Pragma("unroll") for (int _i = 0; _i < 2; ++_i) \
;         __builtin_amdgcn_global_load_lds((const unsigned*)((const char*)(gbase) + (voff)[_i]), (PG8_LAS unsigned*)(lds + (bufoff) + ldsw + _i * 8192), 16, 0, 0); } while (0)
; #define PG8_LDA(dst, b, h) do { _Pragma("unroll") for (int m = 0; m < 4; ++m) _Pragma("unroll") for (int k = 0; k < 2; ++k) dst[m][k] = *(const PG8_LAS bf16x8*)(lds + PG8_SA(b, h) + aoff + m * 2048 + k * 1024); } while (0)
; #define PG8_LDB(dst, b, h) do { _Pragma("unroll") for (int n = 0; n < 2; ++n) _Pragma("unroll") for (int k = 0; k < 2; ++k) dst[n][k] = *(const PG8_LAS bf16x8*)(lds + PG8_SB(b, h) + boff + n * 2048 + k * 1024); } while (0)
; #define PG8_MMA(ai, bj, At, Bt) do { __builtin_amdgcn_s_setprio(1); _Pragma("unroll") for (int m = 0; m < 4; ++m) _Pragma("unroll") for (int n = 0; n < 2; ++n) _Pragma("unroll") for (int k = 0; k < 2; ++k) \
;         acc[ai][bj][m][n] = __builtin_amdgcn_mfma_f32_16x16x32_bf16(Bt[n][k], At[m][k], acc[ai][bj][m][n], 0, 0, 0); __builtin_amdgcn_s_setprio(0); } while (0)
; #define PG8_WAIT_V(n) asm volatile("s_waitcnt vmcnt(" #n ")" ::: "memory")
; #define PG8_WAIT_L(n) asm volatile("s_waitcnt lgkmcnt(" #n ")" ::: "memory")
; #define PG8_BAR __builtin_amdgcn_s_barrier()
; #define PG8_SCHED __builtin_amdgcn_sched_barrier(0)
; template <class Epi, class Sched, bool ALIGN_EPI = false, bool SP2 = false>
; __device__ __forceinline__ void gemm_phase(PG8_LAS unsigned char* lds, const Gemm g, const Sched& S, const Epi& E) {
;     ...
;         for (int t = 0; t < nt; t += 2) {
;     ...
;             PG8_LDB(B0, 1, 0); PG8_LDB(B1, 1, 1); PG8_SCHED; PG8_LDA(At, 1, 0); PG8_STAGE(PG8_SA(0, 1), a2 + hstepA, voffA);
;             PG8_WAIT_V(8); PG8_WAIT_L(0); PG8_BAR; PG8_MMA(0, 0, At, B0); PG8_MMA(0, 1, At, B1); PG8_BAR; PG8_SCHED;
;             PG8_LDA(At, 1, 1); PG8_STAGE(PG8_SB(1, 0), b3, voffB); PG8_STAGE(PG8_SB(1, 1), b3 + hstepB, voffB); PG8_STAGE(PG8_SA(1, 0), a3, voffA);
;             PG8_WAIT_V(8); PG8_WAIT_L(0); PG8_BAR; PG8_MMA(1, 0, At, B0); PG8_MMA(1, 1, At, B1); PG8_BAR; PG8_SCHED;
;     ...
;         if constexpr (ALIGN_EPI) { if (wr == 0) PG8_BAR; }
;         if constexpr (!Epi::AFTER_DRAIN) { E(acc, cur, wr, wc, fr, fq); S.done(cur); }
;         if (!has_next) break;
	s_add_i32 s30, 0, 0x18000
	s_add_i32 s31, 0, 0x1c000
	v_add_u32_e32 v84, s30, v240
	v_add_u32_e32 v116, s31, v240
	ds_read_b128 v[72:75], v84
	ds_read_b128 v[76:79], v84 offset:1024
	ds_read_b128 v[80:83], v84 offset:2048
	ds_read_b128 v[84:87], v84 offset:3072
	ds_read_b128 v[104:107], v116
	ds_read_b128 v[108:111], v116 offset:1024
	ds_read_b128 v[112:115], v116 offset:2048
	ds_read_b128 v[116:119], v116 offset:3072
	s_add_u32 s2, s10, 0x40000
	s_addc_u32 s3, s11, 0
	s_mov_b32 m0, s64
	ds_read_b128 v[140:143], v241 offset:32768
	ds_read_b128 v[144:147], v241 offset:33792
	ds_read_b128 v[148:151], v241 offset:34816
	ds_read_b128 v[168:171], v241 offset:35840
	ds_read_b128 v[172:175], v241 offset:36864
	ds_read_b128 v[176:179], v241 offset:37888
	ds_read_b128 v[180:183], v241 offset:38912
	ds_read_b128 v[208:211], v241 offset:39936
	global_load_lds_dwordx4 v198, s[2:3]
	s_mov_b32 m0, s65
	s_nop 0
	global_load_lds_dwordx4 v200, s[2:3]
	s_waitcnt vmcnt(8)
	s_waitcnt lgkmcnt(0)
	s_barrier
	s_waitcnt lgkmcnt(0)
	v_mfma_f32_16x16x32_bf16 v[160:163], v[72:75], v[140:143], v[188:191]
	v_mfma_f32_16x16x32_bf16 v[188:191], v[76:79], v[144:147], v[160:163]
	v_mfma_f32_16x16x32_bf16 v[160:163], v[80:83], v[140:143], v[184:187]
	v_mfma_f32_16x16x32_bf16 v[156:159], v[72:75], v[148:151], v[156:159]
	v_mfma_f32_16x16x32_bf16 v[152:155], v[80:83], v[148:151], v[152:155]
	v_mfma_f32_16x16x32_bf16 v[124:127], v[72:75], v[172:175], v[124:127]
	v_mfma_f32_16x16x32_bf16 v[120:123], v[80:83], v[172:175], v[120:123]
	v_mfma_f32_16x16x32_bf16 v[92:95], v[72:75], v[180:183], v[92:95]
	v_mfma_f32_16x16x32_bf16 v[88:91], v[80:83], v[180:183], v[88:91]
	v_mfma_f32_16x16x32_bf16 v[184:187], v[84:87], v[144:147], v[160:163]
	v_mfma_f32_16x16x32_bf16 v[156:159], v[76:79], v[168:171], v[156:159]
	v_mfma_f32_16x16x32_bf16 v[152:155], v[84:87], v[168:171], v[152:155]
	v_mfma_f32_16x16x32_bf16 v[124:127], v[76:79], v[176:179], v[124:127]
	v_mfma_f32_16x16x32_bf16 v[120:123], v[84:87], v[176:179], v[120:123]
	v_mfma_f32_16x16x32_bf16 v[92:95], v[76:79], v[208:211], v[92:95]
	v_mfma_f32_16x16x32_bf16 v[88:91], v[84:87], v[208:211], v[88:91]
	v_mfma_f32_16x16x32_bf16 v[160:163], v[104:107], v[140:143], v[164:167]
	v_mfma_f32_16x16x32_bf16 v[136:139], v[112:115], v[140:143], v[136:139]
	v_mfma_f32_16x16x32_bf16 v[132:135], v[104:107], v[148:151], v[132:135]
	v_mfma_f32_16x16x32_bf16 v[128:131], v[112:115], v[148:151], v[128:131]
	v_mfma_f32_16x16x32_bf16 v[100:103], v[104:107], v[172:175], v[100:103]
	v_mfma_f32_16x16x32_bf16 v[96:99], v[112:115], v[172:175], v[96:99]
	v_mfma_f32_16x16x32_bf16 v[68:71], v[104:107], v[180:183], v[68:71]
	v_mfma_f32_16x16x32_bf16 v[64:67], v[112:115], v[180:183], v[64:67]
	v_mfma_f32_16x16x32_bf16 v[164:167], v[108:111], v[144:147], v[160:163]
	v_mfma_f32_16x16x32_bf16 v[160:163], v[116:119], v[144:147], v[136:139]
	v_mfma_f32_16x16x32_bf16 v[132:135], v[108:111], v[168:171], v[132:135]
	v_mfma_f32_16x16x32_bf16 v[128:131], v[116:119], v[168:171], v[128:131]
	v_mfma_f32_16x16x32_bf16 v[100:103], v[108:111], v[176:179], v[100:103]
	v_mfma_f32_16x16x32_bf16 v[96:99], v[116:119], v[176:179], v[96:99]
	v_mfma_f32_16x16x32_bf16 v[68:71], v[108:111], v[208:211], v[68:71]
	v_mfma_f32_16x16x32_bf16 v[64:67], v[116:119], v[208:211], v[64:67]
	s_barrier
	s_add_i32 s2, s30, s18
	s_add_i32 m0, s2, 0xffffff80
	ds_read_b128 v[136:139], v241 offset:49152
	ds_read_b128 v[140:143], v241 offset:50176
	ds_read_b128 v[144:147], v241 offset:51200
	ds_read_b128 v[148:151], v241 offset:52224
	ds_read_b128 v[168:171], v241 offset:53248
	ds_read_b128 v[172:175], v241 offset:54272
	ds_read_b128 v[176:179], v241 offset:55296
	ds_read_b128 v[180:183], v241 offset:56320
	global_load_lds_dwordx4 v192, s[8:9] offset:128
	s_add_i32 m0, s2, 0x1f80
	s_add_u32 s2, s8, 0x40080
	global_load_lds_dwordx4 v202, s[8:9] offset:128
	s_addc_u32 s3, s9, 0
	s_add_i32 s8, s31, s18
	s_mov_b32 m0, s8
	s_nop 0
	global_load_lds_dwordx4 v192, s[2:3]
	s_add_i32 m0, s8, 0x2000
	s_nop 0
	global_load_lds_dwordx4 v202, s[2:3]
	s_add_i32 m0, s21, 0xffffff80
	s_nop 0
	global_load_lds_dwordx4 v198, s[10:11] offset:128
	s_add_i32 m0, s62, 0xffffff80
	s_nop 0
	global_load_lds_dwordx4 v200, s[10:11] offset:128
	s_waitcnt vmcnt(8)
	s_waitcnt lgkmcnt(0)
	s_barrier
	s_waitcnt lgkmcnt(0)
	v_mfma_f32_16x16x32_bf16 v[60:63], v[72:75], v[136:139], v[60:63]
	v_mfma_f32_16x16x32_bf16 v[56:59], v[80:83], v[136:139], v[56:59]
	v_mfma_f32_16x16x32_bf16 v[44:47], v[72:75], v[144:147], v[44:47]
	v_mfma_f32_16x16x32_bf16 v[40:43], v[80:83], v[144:147], v[40:43]
	v_mfma_f32_16x16x32_bf16 v[28:31], v[72:75], v[168:171], v[28:31]
	v_mfma_f32_16x16x32_bf16 v[24:27], v[80:83], v[168:171], v[24:27]
	v_mfma_f32_16x16x32_bf16 v[12:15], v[72:75], v[176:179], v[12:15]
	v_mfma_f32_16x16x32_bf16 v[8:11], v[80:83], v[176:179], v[8:11]
	v_mfma_f32_16x16x32_bf16 v[60:63], v[76:79], v[140:143], v[60:63]
	v_mfma_f32_16x16x32_bf16 v[56:59], v[84:87], v[140:143], v[56:59]
	v_mfma_f32_16x16x32_bf16 v[44:47], v[76:79], v[148:151], v[44:47]
	v_mfma_f32_16x16x32_bf16 v[40:43], v[84:87], v[148:151], v[40:43]
	v_mfma_f32_16x16x32_bf16 v[28:31], v[76:79], v[172:175], v[28:31]
	v_mfma_f32_16x16x32_bf16 v[24:27], v[84:87], v[172:175], v[24:27]
	v_mfma_f32_16x16x32_bf16 v[12:15], v[76:79], v[180:183], v[12:15]
	v_mfma_f32_16x16x32_bf16 v[8:11], v[84:87], v[180:183], v[8:11]
	v_mfma_f32_16x16x32_bf16 v[52:55], v[104:107], v[136:139], v[52:55]
	v_mfma_f32_16x16x32_bf16 v[48:51], v[112:115], v[136:139], v[48:51]
	v_mfma_f32_16x16x32_bf16 v[36:39], v[104:107], v[144:147], v[36:39]
	v_mfma_f32_16x16x32_bf16 v[32:35], v[112:115], v[144:147], v[32:35]
	v_mfma_f32_16x16x32_bf16 v[20:23], v[104:107], v[168:171], v[20:23]
	v_mfma_f32_16x16x32_bf16 v[16:19], v[112:115], v[168:171], v[16:19]
	v_mfma_f32_16x16x32_bf16 v[4:7], v[104:107], v[176:179], v[4:7]
	v_mfma_f32_16x16x32_bf16 v[0:3], v[112:115], v[176:179], v[0:3]
	v_mfma_f32_16x16x32_bf16 v[52:55], v[108:111], v[140:143], v[52:55]
	v_mfma_f32_16x16x32_bf16 v[48:51], v[116:119], v[140:143], v[48:51]
	v_mfma_f32_16x16x32_bf16 v[36:39], v[108:111], v[148:151], v[36:39]
	v_mfma_f32_16x16x32_bf16 v[32:35], v[116:119], v[148:151], v[32:35]
	v_mfma_f32_16x16x32_bf16 v[20:23], v[108:111], v[172:175], v[20:23]
	v_mfma_f32_16x16x32_bf16 v[16:19], v[116:119], v[172:175], v[16:19]
	v_mfma_f32_16x16x32_bf16 v[4:7], v[108:111], v[180:183], v[4:7]
	v_mfma_f32_16x16x32_bf16 v[0:3], v[116:119], v[180:183], v[0:3]
	s_barrier
	s_add_i32 s78, s78, 2
	s_add_u32 s16, s16, 0x100
	s_addc_u32 s17, s17, 0
	s_add_u32 s0, s0, 0x100
	s_addc_u32 s1, s1, 0
	s_cmp_gt_u32 s78, 13
	s_cbranch_scc0 .LBB0_817
	s_and_b64 vcc, exec, s[66:67]
	s_cbranch_vccz .LBB0_820
	s_barrier
